# n=1 conv weights prefetched into dead accumulator quads; P6 start offset 3 sleeps
# baseline (speedup 1.0000x reference)
; #define LAS __attribute__((address_space(3)))
; __global__ void __launch_bounds__(512, 2) fwd_megakernel(Args a) {
;     ...
;     PHASE_IDS();
;     {
;         pg8::Gemm g{X1B, WUP, DM, DM}; pg8::StaticOrder S; S.init(MT, FF2, DM, G, bx);
;         pg8::EpiUp E{ACT, HT, UPS, SSQ2, w_ffn_conv, b_ffn_conv, (LAS float*)(ldsl + LDS_HALO)};
;         pg8::gemm_phase<pg8::EpiUp, pg8::StaticOrder>(ldsl, g, S, E);
.LBB0_911:
	s_or_b64 exec, exec, s[4:5]
	s_cmpk_lt_i32 s68, 0xb2c
	s_cselect_b64 s[4:5], -1, 0
	s_waitcnt lgkmcnt(0)
	v_mov_b32_e32 v0, v228
	v_mov_b32_e32 v8, v228
	s_barrier
	v_readlane_b32 vcc_lo, v254, 9
	s_nop 3
	s_cmp_lt_u32 vcc_lo, 128
	s_cbranch_scc1 .Lstag_done_P6
	s_sleep 127
	s_sleep 127
	s_sleep 127
.Lstag_done_P6:
	s_and_b64 vcc, exec, s[4:5]
	v_readfirstlane_b32 s0, v8
	s_cbranch_vccz .LBB0_913
	s_mul_i32 s2, s75, 0x165
	s_add_i32 s2, s2, 4
	s_mul_i32 s1, s75, 0x166
	s_cmp_lt_i32 s75, 4
	s_cselect_b32 s1, s1, s2
	v_readlane_b32 s2, v254, 8
	s_add_i32 s1, s1, s2
	s_mul_hi_i32 s2, s1, 0x2e8ba2e9
	s_lshr_b32 s3, s2, 31
	s_ashr_i32 s2, s2, 5
	s_add_i32 s2, s2, s3
	s_lshl_b32 s6, s2, 3
	s_sub_i32 s3, 0x82, s6
	s_min_u32 s7, s3, 8
	s_mulk_i32 s2, 0xb0
	s_sub_i32 s1, s1, s2
	v_cvt_f32_ubyte0_e32 v1, s7
	v_cvt_f32_i32_e32 v0, s1
	v_rcp_iflag_f32_e32 v2, v1
	s_ashr_i32 s2, s1, 30
	s_or_b32 s8, s2, 1
	v_mul_f32_e32 v2, v0, v2
	v_trunc_f32_e32 v2, v2
	v_fma_f32 v0, -v2, v1, v0
	v_cvt_i32_f32_e32 v2, v2
	v_cmp_ge_f32_e64 s[2:3], |v0|, v1
	s_and_b64 s[2:3], s[2:3], exec
	s_cselect_b32 s2, s8, 0
	v_readfirstlane_b32 s3, v2
	s_add_i32 s2, s3, s2
	s_sext_i32_i16 s14, s2
	s_mul_i32 s2, s2, s7
	s_sub_i32 s1, s1, s2
	s_sext_i32_i16 s1, s1
	s_add_i32 s42, s6, s1

; #define LAS __attribute__((address_space(3)))
; __device__ __forceinline__ unsigned cvt_pk_bf16(float lo, float hi) { const f32x2 v = {lo, hi}; return __builtin_bit_cast(unsigned, __builtin_convertvector(v, bf16x2_t)); }
;     __device__ __forceinline__ void operator()(Acc& acc, const Unit& u, int wr, int wc, int fr, int fq) const {
;     ...
;             for (int ai = 0; ai < 2; ++ai) {
;                 const int s = ai * 2 + wr;
;                 f32x4 ha = (f32x4){0.f, 0.f, 0.f, 0.f}, hb = ha;
;                 if (s > 0 && fr >= 14) { ha = *(const LAS f32x4*)(halo + (((s - 1) * 2 + (fr - 14)) * 2 + 0) * HALF + cl + 4 * n);
;                                           hb = *(const LAS f32x4*)(halo + (((s - 1) * 2 + (fr - 14)) * 2 + 1) * HALF + cl + 4 * n); }
; #pragma unroll
;                 for (int m = 0; m < 4; ++m) {
;                     const f32x4 ca = acc[ai][0][m][n], cbv = acc[ai][1][m][n];
;                     const f32x4 pa = (m > 0) ? acc[ai][0][m > 0 ? m - 1 : 0][n] : ha, pb = (m > 0) ? acc[ai][1][m > 0 ? m - 1 : 0][n] : hb;
;                     float res[4];
; #pragma unroll
;                     for (int e = 0; e < 4; ++e) {
;                         const float a1 = dpp_prev1(ca[e], pa[e]), a2 = dpp_prev2(ca[e], pa[e]);
;                         const float b1 = dpp_prev1(cbv[e], pb[e]), b2 = dpp_prev2(cbv[e], pb[e]);
;                         const float ua = bba[e] + w0a[e] * a2 + w1a[e] * a1 + w2a[e] * ca[e];
;                         const float ub = bbb[e] + w0b[e] * b2 + w1b[e] * b1 + w2b[e] * cbv[e];
;                         res[e] = gelu_tanh(ua) * ub; }
;                     const int row = row0 + ai * HALF + m * 16;
;                     u32x2 w; w.x = cvt_pk_bf16(res[0], res[1]); w.y = cvt_pk_bf16(res[2], res[3]);
;                     *(u32x2*)(act + (size_t)row * FF + col) = w;
.Lcv_h00:
	s_or_b64 exec, exec, s[56:57]
	s_waitcnt vmcnt(0) lgkmcnt(0)
	v_pk_fma_f32 v[176:177], v[8:9], v[152:153], v[156:157]
	v_pk_fma_f32 v[178:179], v[10:11], v[154:155], v[158:159]
	v_pk_fma_f32 v[180:181], v[0:1], v[136:137], v[140:141]
	v_pk_fma_f32 v[182:183], v[2:3], v[138:139], v[142:143]
	v_fmac_f32_dpp v176, v8, v148 row_shr:1 row_mask:0xf bank_mask:0xf bound_ctrl:1
	v_fmac_f32_dpp v177, v9, v149 row_shr:1 row_mask:0xf bank_mask:0xf bound_ctrl:1
	v_fmac_f32_dpp v178, v10, v150 row_shr:1 row_mask:0xf bank_mask:0xf bound_ctrl:1
	v_fmac_f32_dpp v179, v11, v151 row_shr:1 row_mask:0xf bank_mask:0xf bound_ctrl:1
	v_fmac_f32_dpp v176, v8, v144 row_shr:2 row_mask:0xf bank_mask:0xf bound_ctrl:1
	v_fmac_f32_dpp v177, v9, v145 row_shr:2 row_mask:0xf bank_mask:0xf bound_ctrl:1
	v_fmac_f32_dpp v178, v10, v146 row_shr:2 row_mask:0xf bank_mask:0xf bound_ctrl:1
	v_fmac_f32_dpp v179, v11, v147 row_shr:2 row_mask:0xf bank_mask:0xf bound_ctrl:1
	v_fmac_f32_dpp v176, v160, v148 row_shl:15 row_mask:0xf bank_mask:0xf bound_ctrl:1
	v_fmac_f32_dpp v177, v161, v149 row_shl:15 row_mask:0xf bank_mask:0xf bound_ctrl:1
	v_fmac_f32_dpp v178, v162, v150 row_shl:15 row_mask:0xf bank_mask:0xf bound_ctrl:1
	v_fmac_f32_dpp v179, v163, v151 row_shl:15 row_mask:0xf bank_mask:0xf bound_ctrl:1
	v_fmac_f32_dpp v176, v160, v144 row_shl:14 row_mask:0xf bank_mask:0xf bound_ctrl:1
	v_fmac_f32_dpp v177, v161, v145 row_shl:14 row_mask:0xf bank_mask:0xf bound_ctrl:1
	v_fmac_f32_dpp v178, v162, v146 row_shl:14 row_mask:0xf bank_mask:0xf bound_ctrl:1
	v_fmac_f32_dpp v179, v163, v147 row_shl:14 row_mask:0xf bank_mask:0xf bound_ctrl:1
	v_fmac_f32_dpp v180, v0, v132 row_shr:1 row_mask:0xf bank_mask:0xf bound_ctrl:1
	v_fmac_f32_dpp v181, v1, v133 row_shr:1 row_mask:0xf bank_mask:0xf bound_ctrl:1
	v_fmac_f32_dpp v182, v2, v134 row_shr:1 row_mask:0xf bank_mask:0xf bound_ctrl:1
	v_fmac_f32_dpp v183, v3, v135 row_shr:1 row_mask:0xf bank_mask:0xf bound_ctrl:1
	v_fmac_f32_dpp v180, v0, v128 row_shr:2 row_mask:0xf bank_mask:0xf bound_ctrl:1
	v_fmac_f32_dpp v181, v1, v129 row_shr:2 row_mask:0xf bank_mask:0xf bound_ctrl:1
	v_fmac_f32_dpp v182, v2, v130 row_shr:2 row_mask:0xf bank_mask:0xf bound_ctrl:1
	v_fmac_f32_dpp v183, v3, v131 row_shr:2 row_mask:0xf bank_mask:0xf bound_ctrl:1
	v_fmac_f32_dpp v180, v164, v132 row_shl:15 row_mask:0xf bank_mask:0xf bound_ctrl:1
	v_fmac_f32_dpp v181, v165, v133 row_shl:15 row_mask:0xf bank_mask:0xf bound_ctrl:1
	v_fmac_f32_dpp v182, v166, v134 row_shl:15 row_mask:0xf bank_mask:0xf bound_ctrl:1
	v_fmac_f32_dpp v183, v167, v135 row_shl:15 row_mask:0xf bank_mask:0xf bound_ctrl:1
	v_fmac_f32_dpp v180, v164, v128 row_shl:14 row_mask:0xf bank_mask:0xf bound_ctrl:1
	v_fmac_f32_dpp v181, v165, v129 row_shl:14 row_mask:0xf bank_mask:0xf bound_ctrl:1
	v_fmac_f32_dpp v182, v166, v130 row_shl:14 row_mask:0xf bank_mask:0xf bound_ctrl:1
	v_fmac_f32_dpp v183, v167, v131 row_shl:14 row_mask:0xf bank_mask:0xf bound_ctrl:1
	v_pk_mul_f32 v[184:185], v[176:177], v[176:177]
	v_pk_mul_f32 v[186:187], v[178:179], v[178:179]
	v_pk_fma_f32 v[184:185], v[184:185], v[238:239], v[240:241]
	v_pk_fma_f32 v[186:187], v[186:187], v[238:239], v[240:241]
	v_pk_mul_f32 v[184:185], v[176:177], v[184:185]
	v_pk_mul_f32 v[186:187], v[178:179], v[186:187]
	v_exp_f32_e32 v184, v184
	v_exp_f32_e32 v185, v185
	v_exp_f32_e32 v186, v186
	v_exp_f32_e32 v187, v187
	s_nop 0
	v_pk_add_f32 v[184:185], v[184:185], v[242:243]
	v_pk_add_f32 v[186:187], v[186:187], v[242:243]
	v_rcp_f32_e32 v184, v184
	v_rcp_f32_e32 v185, v185
	v_rcp_f32_e32 v186, v186
	v_rcp_f32_e32 v187, v187
	s_nop 0
	v_pk_mul_f32 v[184:185], v[176:177], v[184:185]
	v_pk_mul_f32 v[186:187], v[178:179], v[186:187]
	v_pk_mul_f32 v[184:185], v[184:185], v[180:181]
	v_pk_mul_f32 v[186:187], v[186:187], v[182:183]
	v_cvt_pk_bf16_f32 v170, v184, v185
	v_cvt_pk_bf16_f32 v171, v186, v187
	v_pk_fma_f32 v[176:177], v[24:25], v[152:153], v[156:157]
	v_pk_fma_f32 v[178:179], v[26:27], v[154:155], v[158:159]
	v_pk_fma_f32 v[180:181], v[16:17], v[136:137], v[140:141]
	v_pk_fma_f32 v[182:183], v[18:19], v[138:139], v[142:143]
	v_fmac_f32_dpp v176, v24, v148 row_shr:1 row_mask:0xf bank_mask:0xf bound_ctrl:1
	v_fmac_f32_dpp v177, v25, v149 row_shr:1 row_mask:0xf bank_mask:0xf bound_ctrl:1
	v_fmac_f32_dpp v178, v26, v150 row_shr:1 row_mask:0xf bank_mask:0xf bound_ctrl:1
	v_fmac_f32_dpp v179, v27, v151 row_shr:1 row_mask:0xf bank_mask:0xf bound_ctrl:1
	v_fmac_f32_dpp v176, v24, v144 row_shr:2 row_mask:0xf bank_mask:0xf bound_ctrl:1
	v_fmac_f32_dpp v177, v25, v145 row_shr:2 row_mask:0xf bank_mask:0xf bound_ctrl:1
	v_fmac_f32_dpp v178, v26, v146 row_shr:2 row_mask:0xf bank_mask:0xf bound_ctrl:1
	v_fmac_f32_dpp v179, v27, v147 row_shr:2 row_mask:0xf bank_mask:0xf bound_ctrl:1
	v_fmac_f32_dpp v176, v8, v148 row_shl:15 row_mask:0xf bank_mask:0xf bound_ctrl:1
	v_fmac_f32_dpp v177, v9, v149 row_shl:15 row_mask:0xf bank_mask:0xf bound_ctrl:1
	v_fmac_f32_dpp v178, v10, v150 row_shl:15 row_mask:0xf bank_mask:0xf bound_ctrl:1
	v_fmac_f32_dpp v179, v11, v151 row_shl:15 row_mask:0xf bank_mask:0xf bound_ctrl:1
	v_fmac_f32_dpp v176, v8, v144 row_shl:14 row_mask:0xf bank_mask:0xf bound_ctrl:1
	v_fmac_f32_dpp v177, v9, v145 row_shl:14 row_mask:0xf bank_mask:0xf bound_ctrl:1
	v_fmac_f32_dpp v178, v10, v146 row_shl:14 row_mask:0xf bank_mask:0xf bound_ctrl:1
	v_fmac_f32_dpp v179, v11, v147 row_shl:14 row_mask:0xf bank_mask:0xf bound_ctrl:1
	v_fmac_f32_dpp v180, v16, v132 row_shr:1 row_mask:0xf bank_mask:0xf bound_ctrl:1
	v_fmac_f32_dpp v181, v17, v133 row_shr:1 row_mask:0xf bank_mask:0xf bound_ctrl:1
	v_fmac_f32_dpp v182, v18, v134 row_shr:1 row_mask:0xf bank_mask:0xf bound_ctrl:1
; #define LAS __attribute__((address_space(3)))
; __device__ __forceinline__ unsigned cvt_pk_bf16(float lo, float hi) { const f32x2 v = {lo, hi}; return __builtin_bit_cast(unsigned, __builtin_convertvector(v, bf16x2_t)); }
;     __device__ __forceinline__ void operator()(Acc& acc, const Unit& u, int wr, int wc, int fr, int fq) const {
;     ...
;             for (int ai = 0; ai < 2; ++ai) {
;                 const int s = ai * 2 + wr;
;                 f32x4 ha = (f32x4){0.f, 0.f, 0.f, 0.f}, hb = ha;
;                 if (s > 0 && fr >= 14) { ha = *(const LAS f32x4*)(halo + (((s - 1) * 2 + (fr - 14)) * 2 + 0) * HALF + cl + 4 * n);
;                                           hb = *(const LAS f32x4*)(halo + (((s - 1) * 2 + (fr - 14)) * 2 + 1) * HALF + cl + 4 * n); }
; #pragma unroll
;                 for (int m = 0; m < 4; ++m) {
;                     const f32x4 ca = acc[ai][0][m][n], cbv = acc[ai][1][m][n];
;                     const f32x4 pa = (m > 0) ? acc[ai][0][m > 0 ? m - 1 : 0][n] : ha, pb = (m > 0) ? acc[ai][1][m > 0 ? m - 1 : 0][n] : hb;
;                     float res[4];
; #pragma unroll
;                     for (int e = 0; e < 4; ++e) {
;                         const float a1 = dpp_prev1(ca[e], pa[e]), a2 = dpp_prev2(ca[e], pa[e]);
;                         const float b1 = dpp_prev1(cbv[e], pb[e]), b2 = dpp_prev2(cbv[e], pb[e]);
;                         const float ua = bba[e] + w0a[e] * a2 + w1a[e] * a1 + w2a[e] * ca[e];
;                         const float ub = bbb[e] + w0b[e] * b2 + w1b[e] * b1 + w2b[e] * cbv[e];
;                         res[e] = gelu_tanh(ua) * ub; }
;                     const int row = row0 + ai * HALF + m * 16;
;                     u32x2 w; w.x = cvt_pk_bf16(res[0], res[1]); w.y = cvt_pk_bf16(res[2], res[3]);
;                     *(u32x2*)(act + (size_t)row * FF + col) = w;
	v_fmac_f32_dpp v183, v19, v135 row_shr:1 row_mask:0xf bank_mask:0xf bound_ctrl:1
	v_fmac_f32_dpp v180, v16, v128 row_shr:2 row_mask:0xf bank_mask:0xf bound_ctrl:1
	v_fmac_f32_dpp v181, v17, v129 row_shr:2 row_mask:0xf bank_mask:0xf bound_ctrl:1
	v_fmac_f32_dpp v182, v18, v130 row_shr:2 row_mask:0xf bank_mask:0xf bound_ctrl:1
	v_fmac_f32_dpp v183, v19, v131 row_shr:2 row_mask:0xf bank_mask:0xf bound_ctrl:1
	v_fmac_f32_dpp v180, v0, v132 row_shl:15 row_mask:0xf bank_mask:0xf bound_ctrl:1
	v_fmac_f32_dpp v181, v1, v133 row_shl:15 row_mask:0xf bank_mask:0xf bound_ctrl:1
	v_fmac_f32_dpp v182, v2, v134 row_shl:15 row_mask:0xf bank_mask:0xf bound_ctrl:1
	v_fmac_f32_dpp v183, v3, v135 row_shl:15 row_mask:0xf bank_mask:0xf bound_ctrl:1
	v_fmac_f32_dpp v180, v0, v128 row_shl:14 row_mask:0xf bank_mask:0xf bound_ctrl:1
	v_fmac_f32_dpp v181, v1, v129 row_shl:14 row_mask:0xf bank_mask:0xf bound_ctrl:1
	v_fmac_f32_dpp v182, v2, v130 row_shl:14 row_mask:0xf bank_mask:0xf bound_ctrl:1
	v_fmac_f32_dpp v183, v3, v131 row_shl:14 row_mask:0xf bank_mask:0xf bound_ctrl:1
	v_pk_mul_f32 v[184:185], v[176:177], v[176:177]
	v_pk_mul_f32 v[186:187], v[178:179], v[178:179]
	v_pk_fma_f32 v[184:185], v[184:185], v[238:239], v[240:241]
	v_pk_fma_f32 v[186:187], v[186:187], v[238:239], v[240:241]
	v_pk_mul_f32 v[184:185], v[176:177], v[184:185]
	v_pk_mul_f32 v[186:187], v[178:179], v[186:187]
	v_exp_f32_e32 v184, v184
	v_exp_f32_e32 v185, v185
	v_exp_f32_e32 v186, v186
	v_exp_f32_e32 v187, v187
	s_nop 0
	v_pk_add_f32 v[184:185], v[184:185], v[242:243]
	v_pk_add_f32 v[186:187], v[186:187], v[242:243]
	v_rcp_f32_e32 v184, v184
	v_rcp_f32_e32 v185, v185
	v_rcp_f32_e32 v186, v186
	v_rcp_f32_e32 v187, v187
	s_nop 0
	v_pk_mul_f32 v[184:185], v[176:177], v[184:185]
	v_pk_mul_f32 v[186:187], v[178:179], v[186:187]
	v_pk_mul_f32 v[184:185], v[184:185], v[180:181]
	v_pk_mul_f32 v[186:187], v[186:187], v[182:183]
	v_cvt_pk_bf16_f32 v172, v184, v185
	v_cvt_pk_bf16_f32 v173, v186, v187
	v_pk_fma_f32 v[176:177], v[40:41], v[152:153], v[156:157]
	v_pk_fma_f32 v[178:179], v[42:43], v[154:155], v[158:159]
	v_pk_fma_f32 v[180:181], v[32:33], v[136:137], v[140:141]
	v_pk_fma_f32 v[182:183], v[34:35], v[138:139], v[142:143]
	v_fmac_f32_dpp v176, v40, v148 row_shr:1 row_mask:0xf bank_mask:0xf bound_ctrl:1
	v_fmac_f32_dpp v177, v41, v149 row_shr:1 row_mask:0xf bank_mask:0xf bound_ctrl:1
	v_fmac_f32_dpp v178, v42, v150 row_shr:1 row_mask:0xf bank_mask:0xf bound_ctrl:1
	v_fmac_f32_dpp v179, v43, v151 row_shr:1 row_mask:0xf bank_mask:0xf bound_ctrl:1
	v_fmac_f32_dpp v176, v40, v144 row_shr:2 row_mask:0xf bank_mask:0xf bound_ctrl:1
	v_fmac_f32_dpp v177, v41, v145 row_shr:2 row_mask:0xf bank_mask:0xf bound_ctrl:1
	v_fmac_f32_dpp v178, v42, v146 row_shr:2 row_mask:0xf bank_mask:0xf bound_ctrl:1
	v_fmac_f32_dpp v179, v43, v147 row_shr:2 row_mask:0xf bank_mask:0xf bound_ctrl:1
	v_fmac_f32_dpp v176, v24, v148 row_shl:15 row_mask:0xf bank_mask:0xf bound_ctrl:1
	v_fmac_f32_dpp v177, v25, v149 row_shl:15 row_mask:0xf bank_mask:0xf bound_ctrl:1
	v_fmac_f32_dpp v178, v26, v150 row_shl:15 row_mask:0xf bank_mask:0xf bound_ctrl:1
	v_fmac_f32_dpp v179, v27, v151 row_shl:15 row_mask:0xf bank_mask:0xf bound_ctrl:1
	v_fmac_f32_dpp v176, v24, v144 row_shl:14 row_mask:0xf bank_mask:0xf bound_ctrl:1
	v_fmac_f32_dpp v177, v25, v145 row_shl:14 row_mask:0xf bank_mask:0xf bound_ctrl:1
	v_fmac_f32_dpp v178, v26, v146 row_shl:14 row_mask:0xf bank_mask:0xf bound_ctrl:1
	v_fmac_f32_dpp v179, v27, v147 row_shl:14 row_mask:0xf bank_mask:0xf bound_ctrl:1
	v_fmac_f32_dpp v180, v32, v132 row_shr:1 row_mask:0xf bank_mask:0xf bound_ctrl:1
	v_fmac_f32_dpp v181, v33, v133 row_shr:1 row_mask:0xf bank_mask:0xf bound_ctrl:1
	v_fmac_f32_dpp v182, v34, v134 row_shr:1 row_mask:0xf bank_mask:0xf bound_ctrl:1
	v_fmac_f32_dpp v183, v35, v135 row_shr:1 row_mask:0xf bank_mask:0xf bound_ctrl:1
	v_fmac_f32_dpp v180, v32, v128 row_shr:2 row_mask:0xf bank_mask:0xf bound_ctrl:1
	v_fmac_f32_dpp v181, v33, v129 row_shr:2 row_mask:0xf bank_mask:0xf bound_ctrl:1
	v_fmac_f32_dpp v182, v34, v130 row_shr:2 row_mask:0xf bank_mask:0xf bound_ctrl:1
	v_fmac_f32_dpp v183, v35, v131 row_shr:2 row_mask:0xf bank_mask:0xf bound_ctrl:1
	v_fmac_f32_dpp v180, v16, v132 row_shl:15 row_mask:0xf bank_mask:0xf bound_ctrl:1
	v_fmac_f32_dpp v181, v17, v133 row_shl:15 row_mask:0xf bank_mask:0xf bound_ctrl:1
	v_fmac_f32_dpp v182, v18, v134 row_shl:15 row_mask:0xf bank_mask:0xf bound_ctrl:1
	v_fmac_f32_dpp v183, v19, v135 row_shl:15 row_mask:0xf bank_mask:0xf bound_ctrl:1
	v_fmac_f32_dpp v180, v16, v128 row_shl:14 row_mask:0xf bank_mask:0xf bound_ctrl:1
	v_fmac_f32_dpp v181, v17, v129 row_shl:14 row_mask:0xf bank_mask:0xf bound_ctrl:1
	v_fmac_f32_dpp v182, v18, v130 row_shl:14 row_mask:0xf bank_mask:0xf bound_ctrl:1
	v_fmac_f32_dpp v183, v19, v131 row_shl:14 row_mask:0xf bank_mask:0xf bound_ctrl:1
	v_pk_mul_f32 v[184:185], v[176:177], v[176:177]
	v_pk_mul_f32 v[186:187], v[178:179], v[178:179]
	v_pk_fma_f32 v[184:185], v[184:185], v[238:239], v[240:241]
	v_pk_fma_f32 v[186:187], v[186:187], v[238:239], v[240:241]
	v_pk_mul_f32 v[184:185], v[176:177], v[184:185]
	v_pk_mul_f32 v[186:187], v[178:179], v[186:187]
	v_exp_f32_e32 v184, v184
	v_exp_f32_e32 v185, v185
	v_exp_f32_e32 v186, v186
	v_exp_f32_e32 v187, v187
	s_nop 0
	v_pk_add_f32 v[184:185], v[184:185], v[242:243]
	v_pk_add_f32 v[186:187], v[186:187], v[242:243]
	v_rcp_f32_e32 v184, v184
	v_rcp_f32_e32 v185, v185
	v_rcp_f32_e32 v186, v186
	v_rcp_f32_e32 v187, v187
	s_nop 0
	v_pk_mul_f32 v[184:185], v[176:177], v[184:185]
	v_pk_mul_f32 v[186:187], v[178:179], v[186:187]
	v_pk_mul_f32 v[184:185], v[184:185], v[180:181]
; #define LAS __attribute__((address_space(3)))
; __device__ __forceinline__ unsigned cvt_pk_bf16(float lo, float hi) { const f32x2 v = {lo, hi}; return __builtin_bit_cast(unsigned, __builtin_convertvector(v, bf16x2_t)); }
;     __device__ __forceinline__ void operator()(Acc& acc, const Unit& u, int wr, int wc, int fr, int fq) const {
;     ...
;             const int col = u.pn * HALF + cl + 4 * n;
;             const f32x4 w0a = *(const f32x4*)(cw + col), w1a = *(const f32x4*)(cw + FF2 + col), w2a = *(const f32x4*)(cw + 2 * FF2 + col), bba = *(const f32x4*)(cb + col);
;             const f32x4 w0b = *(const f32x4*)(cw + FF + col), w1b = *(const f32x4*)(cw + FF2 + FF + col), w2b = *(const f32x4*)(cw + 2 * FF2 + FF + col), bbb = *(const f32x4*)(cb + FF + col);
; #pragma unroll
;             for (int ai = 0; ai < 2; ++ai) {
;                 const int s = ai * 2 + wr;
;                 f32x4 ha = (f32x4){0.f, 0.f, 0.f, 0.f}, hb = ha;
;                 if (s > 0 && fr >= 14) { ha = *(const LAS f32x4*)(halo + (((s - 1) * 2 + (fr - 14)) * 2 + 0) * HALF + cl + 4 * n);
;                                           hb = *(const LAS f32x4*)(halo + (((s - 1) * 2 + (fr - 14)) * 2 + 1) * HALF + cl + 4 * n); }
; #pragma unroll
;                 for (int m = 0; m < 4; ++m) {
;                     const f32x4 ca = acc[ai][0][m][n], cbv = acc[ai][1][m][n];
;                     const f32x4 pa = (m > 0) ? acc[ai][0][m > 0 ? m - 1 : 0][n] : ha, pb = (m > 0) ? acc[ai][1][m > 0 ? m - 1 : 0][n] : hb;
;                     float res[4];
; #pragma unroll
;                     for (int e = 0; e < 4; ++e) {
;                         const float a1 = dpp_prev1(ca[e], pa[e]), a2 = dpp_prev2(ca[e], pa[e]);
;                         const float b1 = dpp_prev1(cbv[e], pb[e]), b2 = dpp_prev2(cbv[e], pb[e]);
;                         const float ua = bba[e] + w0a[e] * a2 + w1a[e] * a1 + w2a[e] * ca[e];
;                         const float ub = bbb[e] + w0b[e] * b2 + w1b[e] * b1 + w2b[e] * cbv[e];
;                         res[e] = gelu_tanh(ua) * ub; }
;                     const int row = row0 + ai * HALF + m * 16;
;                     u32x2 w; w.x = cvt_pk_bf16(res[0], res[1]); w.y = cvt_pk_bf16(res[2], res[3]);
;                     *(u32x2*)(act + (size_t)row * FF + col) = w;
	v_pk_mul_f32 v[186:187], v[186:187], v[182:183]
	v_cvt_pk_bf16_f32 v174, v184, v185
	v_cvt_pk_bf16_f32 v175, v186, v187
	v_pk_fma_f32 v[176:177], v[56:57], v[152:153], v[156:157]
	v_pk_fma_f32 v[178:179], v[58:59], v[154:155], v[158:159]
	v_pk_fma_f32 v[180:181], v[48:49], v[136:137], v[140:141]
	v_pk_fma_f32 v[182:183], v[50:51], v[138:139], v[142:143]
	v_fmac_f32_dpp v176, v56, v148 row_shr:1 row_mask:0xf bank_mask:0xf bound_ctrl:1
	v_fmac_f32_dpp v177, v57, v149 row_shr:1 row_mask:0xf bank_mask:0xf bound_ctrl:1
	v_fmac_f32_dpp v178, v58, v150 row_shr:1 row_mask:0xf bank_mask:0xf bound_ctrl:1
	v_fmac_f32_dpp v179, v59, v151 row_shr:1 row_mask:0xf bank_mask:0xf bound_ctrl:1
	v_fmac_f32_dpp v176, v56, v144 row_shr:2 row_mask:0xf bank_mask:0xf bound_ctrl:1
	v_fmac_f32_dpp v177, v57, v145 row_shr:2 row_mask:0xf bank_mask:0xf bound_ctrl:1
	v_fmac_f32_dpp v178, v58, v146 row_shr:2 row_mask:0xf bank_mask:0xf bound_ctrl:1
	v_fmac_f32_dpp v179, v59, v147 row_shr:2 row_mask:0xf bank_mask:0xf bound_ctrl:1
	v_fmac_f32_dpp v176, v40, v148 row_shl:15 row_mask:0xf bank_mask:0xf bound_ctrl:1
	v_fmac_f32_dpp v177, v41, v149 row_shl:15 row_mask:0xf bank_mask:0xf bound_ctrl:1
	v_fmac_f32_dpp v178, v42, v150 row_shl:15 row_mask:0xf bank_mask:0xf bound_ctrl:1
	v_fmac_f32_dpp v179, v43, v151 row_shl:15 row_mask:0xf bank_mask:0xf bound_ctrl:1
	v_fmac_f32_dpp v176, v40, v144 row_shl:14 row_mask:0xf bank_mask:0xf bound_ctrl:1
	v_fmac_f32_dpp v177, v41, v145 row_shl:14 row_mask:0xf bank_mask:0xf bound_ctrl:1
	v_fmac_f32_dpp v178, v42, v146 row_shl:14 row_mask:0xf bank_mask:0xf bound_ctrl:1
	v_fmac_f32_dpp v179, v43, v147 row_shl:14 row_mask:0xf bank_mask:0xf bound_ctrl:1
	v_fmac_f32_dpp v180, v48, v132 row_shr:1 row_mask:0xf bank_mask:0xf bound_ctrl:1
	v_fmac_f32_dpp v181, v49, v133 row_shr:1 row_mask:0xf bank_mask:0xf bound_ctrl:1
	v_fmac_f32_dpp v182, v50, v134 row_shr:1 row_mask:0xf bank_mask:0xf bound_ctrl:1
	v_fmac_f32_dpp v183, v51, v135 row_shr:1 row_mask:0xf bank_mask:0xf bound_ctrl:1
	v_fmac_f32_dpp v180, v48, v128 row_shr:2 row_mask:0xf bank_mask:0xf bound_ctrl:1
	v_fmac_f32_dpp v181, v49, v129 row_shr:2 row_mask:0xf bank_mask:0xf bound_ctrl:1
	v_fmac_f32_dpp v182, v50, v130 row_shr:2 row_mask:0xf bank_mask:0xf bound_ctrl:1
	v_fmac_f32_dpp v183, v51, v131 row_shr:2 row_mask:0xf bank_mask:0xf bound_ctrl:1
	v_fmac_f32_dpp v180, v32, v132 row_shl:15 row_mask:0xf bank_mask:0xf bound_ctrl:1
	v_fmac_f32_dpp v181, v33, v133 row_shl:15 row_mask:0xf bank_mask:0xf bound_ctrl:1
	v_fmac_f32_dpp v182, v34, v134 row_shl:15 row_mask:0xf bank_mask:0xf bound_ctrl:1
	v_fmac_f32_dpp v183, v35, v135 row_shl:15 row_mask:0xf bank_mask:0xf bound_ctrl:1
	v_fmac_f32_dpp v180, v32, v128 row_shl:14 row_mask:0xf bank_mask:0xf bound_ctrl:1
	v_fmac_f32_dpp v181, v33, v129 row_shl:14 row_mask:0xf bank_mask:0xf bound_ctrl:1
	v_fmac_f32_dpp v182, v34, v130 row_shl:14 row_mask:0xf bank_mask:0xf bound_ctrl:1
	v_fmac_f32_dpp v183, v35, v131 row_shl:14 row_mask:0xf bank_mask:0xf bound_ctrl:1
	v_pk_mul_f32 v[184:185], v[176:177], v[176:177]
	v_pk_mul_f32 v[186:187], v[178:179], v[178:179]
	v_pk_fma_f32 v[184:185], v[184:185], v[238:239], v[240:241]
	v_pk_fma_f32 v[186:187], v[186:187], v[238:239], v[240:241]
	v_pk_mul_f32 v[184:185], v[176:177], v[184:185]
	v_pk_mul_f32 v[186:187], v[178:179], v[186:187]
	v_exp_f32_e32 v184, v184
	v_exp_f32_e32 v185, v185
	v_exp_f32_e32 v186, v186
	v_exp_f32_e32 v187, v187
	s_nop 0
	v_pk_add_f32 v[184:185], v[184:185], v[242:243]
	v_pk_add_f32 v[186:187], v[186:187], v[242:243]
	v_rcp_f32_e32 v184, v184
	v_rcp_f32_e32 v185, v185
	v_rcp_f32_e32 v186, v186
	v_rcp_f32_e32 v187, v187
	s_nop 0
	v_pk_mul_f32 v[184:185], v[176:177], v[184:185]
	v_pk_mul_f32 v[186:187], v[178:179], v[186:187]
	v_pk_mul_f32 v[184:185], v[184:185], v[180:181]
	v_pk_mul_f32 v[186:187], v[186:187], v[182:183]
	v_cvt_pk_bf16_f32 v237, v184, v185
	v_cvt_pk_bf16_f32 v248, v186, v187
	global_load_dwordx4 v[8:11], v245, s[8:9] offset:16
	global_load_dwordx4 v[24:27], v245, s[30:31] offset:16
	global_load_dwordx4 v[40:43], v245, s[34:35] offset:16
	global_load_dwordx4 v[56:59], v245, s[10:11] offset:16
	global_load_dwordx4 v[0:3], v245, s[36:37] offset:16
	global_load_dwordx4 v[16:19], v245, s[38:39] offset:16
	global_load_dwordx4 v[32:35], v245, s[40:41] offset:16
	global_load_dwordx4 v[48:51], v245, s[44:45] offset:16
	v_mov_b32_e32 v160, 0
	v_mov_b32_e32 v161, 0
	v_mov_b32_e32 v162, 0
	v_mov_b32_e32 v163, 0
	v_mov_b32_e32 v164, 0
	v_mov_b32_e32 v165, 0
	v_mov_b32_e32 v166, 0
	v_mov_b32_e32 v167, 0
	s_and_b64 s[42:43], s[28:29], s[6:7]
	s_and_saveexec_b64 s[56:57], s[42:43]
	s_cbranch_execz .Lcv_h01
	v_add_u32_e32 v168, 0xffffd000, v244
	v_add_u32_e32 v169, 0xffffd200, v244
	ds_read_b128 v[160:163], v168
	ds_read_b128 v[164:167], v169
; #define LAS __attribute__((address_space(3)))
; __device__ __forceinline__ unsigned cvt_pk_bf16(float lo, float hi) { const f32x2 v = {lo, hi}; return __builtin_bit_cast(unsigned, __builtin_convertvector(v, bf16x2_t)); }
;     __device__ __forceinline__ void operator()(Acc& acc, const Unit& u, int wr, int wc, int fr, int fq) const {
;     ...
;             for (int ai = 0; ai < 2; ++ai) {
;                 const int s = ai * 2 + wr;
;                 f32x4 ha = (f32x4){0.f, 0.f, 0.f, 0.f}, hb = ha;
;                 if (s > 0 && fr >= 14) { ha = *(const LAS f32x4*)(halo + (((s - 1) * 2 + (fr - 14)) * 2 + 0) * HALF + cl + 4 * n);
;                                           hb = *(const LAS f32x4*)(halo + (((s - 1) * 2 + (fr - 14)) * 2 + 1) * HALF + cl + 4 * n); }
; #pragma unroll
;                 for (int m = 0; m < 4; ++m) {
;                     const f32x4 ca = acc[ai][0][m][n], cbv = acc[ai][1][m][n];
;                     const f32x4 pa = (m > 0) ? acc[ai][0][m > 0 ? m - 1 : 0][n] : ha, pb = (m > 0) ? acc[ai][1][m > 0 ? m - 1 : 0][n] : hb;
;                     float res[4];
; #pragma unroll
;                     for (int e = 0; e < 4; ++e) {
;                         const float a1 = dpp_prev1(ca[e], pa[e]), a2 = dpp_prev2(ca[e], pa[e]);
;                         const float b1 = dpp_prev1(cbv[e], pb[e]), b2 = dpp_prev2(cbv[e], pb[e]);
;                         const float ua = bba[e] + w0a[e] * a2 + w1a[e] * a1 + w2a[e] * ca[e];
;                         const float ub = bbb[e] + w0b[e] * b2 + w1b[e] * b1 + w2b[e] * cbv[e];
;                         res[e] = gelu_tanh(ua) * ub; }
;                     const int row = row0 + ai * HALF + m * 16;
;                     u32x2 w; w.x = cvt_pk_bf16(res[0], res[1]); w.y = cvt_pk_bf16(res[2], res[3]);
;                     *(u32x2*)(act + (size_t)row * FF + col) = w;
.Lcv_h01:
	s_or_b64 exec, exec, s[56:57]
	s_waitcnt lgkmcnt(0)
	v_pk_fma_f32 v[176:177], v[64:65], v[152:153], v[156:157]
	v_pk_fma_f32 v[178:179], v[66:67], v[154:155], v[158:159]
	v_pk_fma_f32 v[180:181], v[72:73], v[136:137], v[140:141]
	v_pk_fma_f32 v[182:183], v[74:75], v[138:139], v[142:143]
	v_fmac_f32_dpp v176, v64, v148 row_shr:1 row_mask:0xf bank_mask:0xf bound_ctrl:1
	v_fmac_f32_dpp v177, v65, v149 row_shr:1 row_mask:0xf bank_mask:0xf bound_ctrl:1
	v_fmac_f32_dpp v178, v66, v150 row_shr:1 row_mask:0xf bank_mask:0xf bound_ctrl:1
	v_fmac_f32_dpp v179, v67, v151 row_shr:1 row_mask:0xf bank_mask:0xf bound_ctrl:1
	v_fmac_f32_dpp v176, v64, v144 row_shr:2 row_mask:0xf bank_mask:0xf bound_ctrl:1
	v_fmac_f32_dpp v177, v65, v145 row_shr:2 row_mask:0xf bank_mask:0xf bound_ctrl:1
	v_fmac_f32_dpp v178, v66, v146 row_shr:2 row_mask:0xf bank_mask:0xf bound_ctrl:1
	v_fmac_f32_dpp v179, v67, v147 row_shr:2 row_mask:0xf bank_mask:0xf bound_ctrl:1
	v_fmac_f32_dpp v176, v160, v148 row_shl:15 row_mask:0xf bank_mask:0xf bound_ctrl:1
	v_fmac_f32_dpp v177, v161, v149 row_shl:15 row_mask:0xf bank_mask:0xf bound_ctrl:1
	v_fmac_f32_dpp v178, v162, v150 row_shl:15 row_mask:0xf bank_mask:0xf bound_ctrl:1
	v_fmac_f32_dpp v179, v163, v151 row_shl:15 row_mask:0xf bank_mask:0xf bound_ctrl:1
	v_fmac_f32_dpp v176, v160, v144 row_shl:14 row_mask:0xf bank_mask:0xf bound_ctrl:1
	v_fmac_f32_dpp v177, v161, v145 row_shl:14 row_mask:0xf bank_mask:0xf bound_ctrl:1
	v_fmac_f32_dpp v178, v162, v146 row_shl:14 row_mask:0xf bank_mask:0xf bound_ctrl:1
	v_fmac_f32_dpp v179, v163, v147 row_shl:14 row_mask:0xf bank_mask:0xf bound_ctrl:1
	v_fmac_f32_dpp v180, v72, v132 row_shr:1 row_mask:0xf bank_mask:0xf bound_ctrl:1
	v_fmac_f32_dpp v181, v73, v133 row_shr:1 row_mask:0xf bank_mask:0xf bound_ctrl:1
	v_fmac_f32_dpp v182, v74, v134 row_shr:1 row_mask:0xf bank_mask:0xf bound_ctrl:1
	v_fmac_f32_dpp v183, v75, v135 row_shr:1 row_mask:0xf bank_mask:0xf bound_ctrl:1
	v_fmac_f32_dpp v180, v72, v128 row_shr:2 row_mask:0xf bank_mask:0xf bound_ctrl:1
	v_fmac_f32_dpp v181, v73, v129 row_shr:2 row_mask:0xf bank_mask:0xf bound_ctrl:1
	v_fmac_f32_dpp v182, v74, v130 row_shr:2 row_mask:0xf bank_mask:0xf bound_ctrl:1
	v_fmac_f32_dpp v183, v75, v131 row_shr:2 row_mask:0xf bank_mask:0xf bound_ctrl:1
	v_fmac_f32_dpp v180, v164, v132 row_shl:15 row_mask:0xf bank_mask:0xf bound_ctrl:1
	v_fmac_f32_dpp v181, v165, v133 row_shl:15 row_mask:0xf bank_mask:0xf bound_ctrl:1
	v_fmac_f32_dpp v182, v166, v134 row_shl:15 row_mask:0xf bank_mask:0xf bound_ctrl:1
	v_fmac_f32_dpp v183, v167, v135 row_shl:15 row_mask:0xf bank_mask:0xf bound_ctrl:1
	v_fmac_f32_dpp v180, v164, v128 row_shl:14 row_mask:0xf bank_mask:0xf bound_ctrl:1
	v_fmac_f32_dpp v181, v165, v129 row_shl:14 row_mask:0xf bank_mask:0xf bound_ctrl:1
	v_fmac_f32_dpp v182, v166, v130 row_shl:14 row_mask:0xf bank_mask:0xf bound_ctrl:1
	v_fmac_f32_dpp v183, v167, v131 row_shl:14 row_mask:0xf bank_mask:0xf bound_ctrl:1
	v_pk_mul_f32 v[184:185], v[176:177], v[176:177]
	v_pk_mul_f32 v[186:187], v[178:179], v[178:179]
	v_pk_fma_f32 v[184:185], v[184:185], v[238:239], v[240:241]
	v_pk_fma_f32 v[186:187], v[186:187], v[238:239], v[240:241]
	v_pk_mul_f32 v[184:185], v[176:177], v[184:185]
	v_pk_mul_f32 v[186:187], v[178:179], v[186:187]
	v_exp_f32_e32 v184, v184
	v_exp_f32_e32 v185, v185
	v_exp_f32_e32 v186, v186
	v_exp_f32_e32 v187, v187
	s_nop 0
	v_pk_add_f32 v[184:185], v[184:185], v[242:243]
	v_pk_add_f32 v[186:187], v[186:187], v[242:243]
	v_rcp_f32_e32 v184, v184
	v_rcp_f32_e32 v185, v185
	v_rcp_f32_e32 v186, v186
	v_rcp_f32_e32 v187, v187
	s_nop 0
	v_pk_mul_f32 v[184:185], v[176:177], v[184:185]
	v_pk_mul_f32 v[186:187], v[178:179], v[186:187]
	v_pk_mul_f32 v[184:185], v[184:185], v[180:181]
	v_pk_mul_f32 v[186:187], v[186:187], v[182:183]
	v_cvt_pk_bf16_f32 v249, v184, v185
	v_cvt_pk_bf16_f32 v250, v186, v187
	v_pk_fma_f32 v[176:177], v[80:81], v[152:153], v[156:157]
	v_pk_fma_f32 v[178:179], v[82:83], v[154:155], v[158:159]
	v_pk_fma_f32 v[180:181], v[88:89], v[136:137], v[140:141]
	v_pk_fma_f32 v[182:183], v[90:91], v[138:139], v[142:143]
	v_fmac_f32_dpp v176, v80, v148 row_shr:1 row_mask:0xf bank_mask:0xf bound_ctrl:1
	v_fmac_f32_dpp v177, v81, v149 row_shr:1 row_mask:0xf bank_mask:0xf bound_ctrl:1
	v_fmac_f32_dpp v178, v82, v150 row_shr:1 row_mask:0xf bank_mask:0xf bound_ctrl:1
	v_fmac_f32_dpp v179, v83, v151 row_shr:1 row_mask:0xf bank_mask:0xf bound_ctrl:1
	v_fmac_f32_dpp v176, v80, v144 row_shr:2 row_mask:0xf bank_mask:0xf bound_ctrl:1
	v_fmac_f32_dpp v177, v81, v145 row_shr:2 row_mask:0xf bank_mask:0xf bound_ctrl:1
	v_fmac_f32_dpp v178, v82, v146 row_shr:2 row_mask:0xf bank_mask:0xf bound_ctrl:1
	v_fmac_f32_dpp v179, v83, v147 row_shr:2 row_mask:0xf bank_mask:0xf bound_ctrl:1
	v_fmac_f32_dpp v176, v64, v148 row_shl:15 row_mask:0xf bank_mask:0xf bound_ctrl:1
	v_fmac_f32_dpp v177, v65, v149 row_shl:15 row_mask:0xf bank_mask:0xf bound_ctrl:1
	v_fmac_f32_dpp v178, v66, v150 row_shl:15 row_mask:0xf bank_mask:0xf bound_ctrl:1
	v_fmac_f32_dpp v179, v67, v151 row_shl:15 row_mask:0xf bank_mask:0xf bound_ctrl:1
	v_fmac_f32_dpp v176, v64, v144 row_shl:14 row_mask:0xf bank_mask:0xf bound_ctrl:1
	v_fmac_f32_dpp v177, v65, v145 row_shl:14 row_mask:0xf bank_mask:0xf bound_ctrl:1
	v_fmac_f32_dpp v178, v66, v146 row_shl:14 row_mask:0xf bank_mask:0xf bound_ctrl:1
	v_fmac_f32_dpp v179, v67, v147 row_shl:14 row_mask:0xf bank_mask:0xf bound_ctrl:1
	v_fmac_f32_dpp v180, v88, v132 row_shr:1 row_mask:0xf bank_mask:0xf bound_ctrl:1
	v_fmac_f32_dpp v181, v89, v133 row_shr:1 row_mask:0xf bank_mask:0xf bound_ctrl:1
	v_fmac_f32_dpp v182, v90, v134 row_shr:1 row_mask:0xf bank_mask:0xf bound_ctrl:1
; __device__ __forceinline__ unsigned cvt_pk_bf16(float lo, float hi) { const f32x2 v = {lo, hi}; return __builtin_bit_cast(unsigned, __builtin_convertvector(v, bf16x2_t)); }
;     __device__ __forceinline__ void operator()(Acc& acc, const Unit& u, int wr, int wc, int fr, int fq) const {
;     ...
;                 for (int m = 0; m < 4; ++m) {
;                     const f32x4 ca = acc[ai][0][m][n], cbv = acc[ai][1][m][n];
;                     const f32x4 pa = (m > 0) ? acc[ai][0][m > 0 ? m - 1 : 0][n] : ha, pb = (m > 0) ? acc[ai][1][m > 0 ? m - 1 : 0][n] : hb;
;                     float res[4];
; #pragma unroll
;                     for (int e = 0; e < 4; ++e) {
;                         const float a1 = dpp_prev1(ca[e], pa[e]), a2 = dpp_prev2(ca[e], pa[e]);
;                         const float b1 = dpp_prev1(cbv[e], pb[e]), b2 = dpp_prev2(cbv[e], pb[e]);
;                         const float ua = bba[e] + w0a[e] * a2 + w1a[e] * a1 + w2a[e] * ca[e];
;                         const float ub = bbb[e] + w0b[e] * b2 + w1b[e] * b1 + w2b[e] * cbv[e];
;                         res[e] = gelu_tanh(ua) * ub; }
;                     const int row = row0 + ai * HALF + m * 16;
;                     u32x2 w; w.x = cvt_pk_bf16(res[0], res[1]); w.y = cvt_pk_bf16(res[2], res[3]);
;                     *(u32x2*)(act + (size_t)row * FF + col) = w;
	v_fmac_f32_dpp v183, v91, v135 row_shr:1 row_mask:0xf bank_mask:0xf bound_ctrl:1
	v_fmac_f32_dpp v180, v88, v128 row_shr:2 row_mask:0xf bank_mask:0xf bound_ctrl:1
	v_fmac_f32_dpp v181, v89, v129 row_shr:2 row_mask:0xf bank_mask:0xf bound_ctrl:1
	v_fmac_f32_dpp v182, v90, v130 row_shr:2 row_mask:0xf bank_mask:0xf bound_ctrl:1
	v_fmac_f32_dpp v183, v91, v131 row_shr:2 row_mask:0xf bank_mask:0xf bound_ctrl:1
	v_fmac_f32_dpp v180, v72, v132 row_shl:15 row_mask:0xf bank_mask:0xf bound_ctrl:1
	v_fmac_f32_dpp v181, v73, v133 row_shl:15 row_mask:0xf bank_mask:0xf bound_ctrl:1
	v_fmac_f32_dpp v182, v74, v134 row_shl:15 row_mask:0xf bank_mask:0xf bound_ctrl:1
	v_fmac_f32_dpp v183, v75, v135 row_shl:15 row_mask:0xf bank_mask:0xf bound_ctrl:1
	v_fmac_f32_dpp v180, v72, v128 row_shl:14 row_mask:0xf bank_mask:0xf bound_ctrl:1
	v_fmac_f32_dpp v181, v73, v129 row_shl:14 row_mask:0xf bank_mask:0xf bound_ctrl:1
	v_fmac_f32_dpp v182, v74, v130 row_shl:14 row_mask:0xf bank_mask:0xf bound_ctrl:1
	v_fmac_f32_dpp v183, v75, v131 row_shl:14 row_mask:0xf bank_mask:0xf bound_ctrl:1
	v_pk_mul_f32 v[184:185], v[176:177], v[176:177]
	v_pk_mul_f32 v[186:187], v[178:179], v[178:179]
	v_pk_fma_f32 v[184:185], v[184:185], v[238:239], v[240:241]
	v_pk_fma_f32 v[186:187], v[186:187], v[238:239], v[240:241]
	v_pk_mul_f32 v[184:185], v[176:177], v[184:185]
	v_pk_mul_f32 v[186:187], v[178:179], v[186:187]
	v_exp_f32_e32 v184, v184
	v_exp_f32_e32 v185, v185
	v_exp_f32_e32 v186, v186
	v_exp_f32_e32 v187, v187
	s_nop 0
	v_pk_add_f32 v[184:185], v[184:185], v[242:243]
	v_pk_add_f32 v[186:187], v[186:187], v[242:243]
	v_rcp_f32_e32 v184, v184
	v_rcp_f32_e32 v185, v185
	v_rcp_f32_e32 v186, v186
	v_rcp_f32_e32 v187, v187
	s_nop 0
	v_pk_mul_f32 v[184:185], v[176:177], v[184:185]
	v_pk_mul_f32 v[186:187], v[178:179], v[186:187]
	v_pk_mul_f32 v[184:185], v[184:185], v[180:181]
	v_pk_mul_f32 v[186:187], v[186:187], v[182:183]
	v_cvt_pk_bf16_f32 v251, v184, v185
	v_cvt_pk_bf16_f32 v211, v186, v187
	v_pk_fma_f32 v[176:177], v[96:97], v[152:153], v[156:157]
	v_pk_fma_f32 v[178:179], v[98:99], v[154:155], v[158:159]
	v_pk_fma_f32 v[180:181], v[104:105], v[136:137], v[140:141]
	v_pk_fma_f32 v[182:183], v[106:107], v[138:139], v[142:143]
	v_fmac_f32_dpp v176, v96, v148 row_shr:1 row_mask:0xf bank_mask:0xf bound_ctrl:1
	v_fmac_f32_dpp v177, v97, v149 row_shr:1 row_mask:0xf bank_mask:0xf bound_ctrl:1
	v_fmac_f32_dpp v178, v98, v150 row_shr:1 row_mask:0xf bank_mask:0xf bound_ctrl:1
	v_fmac_f32_dpp v179, v99, v151 row_shr:1 row_mask:0xf bank_mask:0xf bound_ctrl:1
	v_fmac_f32_dpp v176, v96, v144 row_shr:2 row_mask:0xf bank_mask:0xf bound_ctrl:1
	v_fmac_f32_dpp v177, v97, v145 row_shr:2 row_mask:0xf bank_mask:0xf bound_ctrl:1
	v_fmac_f32_dpp v178, v98, v146 row_shr:2 row_mask:0xf bank_mask:0xf bound_ctrl:1
	v_fmac_f32_dpp v179, v99, v147 row_shr:2 row_mask:0xf bank_mask:0xf bound_ctrl:1
	v_fmac_f32_dpp v176, v80, v148 row_shl:15 row_mask:0xf bank_mask:0xf bound_ctrl:1
	v_fmac_f32_dpp v177, v81, v149 row_shl:15 row_mask:0xf bank_mask:0xf bound_ctrl:1
	v_fmac_f32_dpp v178, v82, v150 row_shl:15 row_mask:0xf bank_mask:0xf bound_ctrl:1
	v_fmac_f32_dpp v179, v83, v151 row_shl:15 row_mask:0xf bank_mask:0xf bound_ctrl:1
	v_fmac_f32_dpp v176, v80, v144 row_shl:14 row_mask:0xf bank_mask:0xf bound_ctrl:1
	v_fmac_f32_dpp v177, v81, v145 row_shl:14 row_mask:0xf bank_mask:0xf bound_ctrl:1
	v_fmac_f32_dpp v178, v82, v146 row_shl:14 row_mask:0xf bank_mask:0xf bound_ctrl:1
	v_fmac_f32_dpp v179, v83, v147 row_shl:14 row_mask:0xf bank_mask:0xf bound_ctrl:1
	v_fmac_f32_dpp v180, v104, v132 row_shr:1 row_mask:0xf bank_mask:0xf bound_ctrl:1
	v_fmac_f32_dpp v181, v105, v133 row_shr:1 row_mask:0xf bank_mask:0xf bound_ctrl:1
	v_fmac_f32_dpp v182, v106, v134 row_shr:1 row_mask:0xf bank_mask:0xf bound_ctrl:1
	v_fmac_f32_dpp v183, v107, v135 row_shr:1 row_mask:0xf bank_mask:0xf bound_ctrl:1
	v_fmac_f32_dpp v180, v104, v128 row_shr:2 row_mask:0xf bank_mask:0xf bound_ctrl:1
	v_fmac_f32_dpp v181, v105, v129 row_shr:2 row_mask:0xf bank_mask:0xf bound_ctrl:1
	v_fmac_f32_dpp v182, v106, v130 row_shr:2 row_mask:0xf bank_mask:0xf bound_ctrl:1
	v_fmac_f32_dpp v183, v107, v131 row_shr:2 row_mask:0xf bank_mask:0xf bound_ctrl:1
	v_fmac_f32_dpp v180, v88, v132 row_shl:15 row_mask:0xf bank_mask:0xf bound_ctrl:1
	v_fmac_f32_dpp v181, v89, v133 row_shl:15 row_mask:0xf bank_mask:0xf bound_ctrl:1
	v_fmac_f32_dpp v182, v90, v134 row_shl:15 row_mask:0xf bank_mask:0xf bound_ctrl:1
	v_fmac_f32_dpp v183, v91, v135 row_shl:15 row_mask:0xf bank_mask:0xf bound_ctrl:1
	v_fmac_f32_dpp v180, v88, v128 row_shl:14 row_mask:0xf bank_mask:0xf bound_ctrl:1
	v_fmac_f32_dpp v181, v89, v129 row_shl:14 row_mask:0xf bank_mask:0xf bound_ctrl:1
	v_fmac_f32_dpp v182, v90, v130 row_shl:14 row_mask:0xf bank_mask:0xf bound_ctrl:1
	v_fmac_f32_dpp v183, v91, v131 row_shl:14 row_mask:0xf bank_mask:0xf bound_ctrl:1
	v_pk_mul_f32 v[184:185], v[176:177], v[176:177]
	v_pk_mul_f32 v[186:187], v[178:179], v[178:179]
	v_pk_fma_f32 v[184:185], v[184:185], v[238:239], v[240:241]
	v_pk_fma_f32 v[186:187], v[186:187], v[238:239], v[240:241]
	v_pk_mul_f32 v[184:185], v[176:177], v[184:185]
	v_pk_mul_f32 v[186:187], v[178:179], v[186:187]
	v_exp_f32_e32 v184, v184
	v_exp_f32_e32 v185, v185
	v_exp_f32_e32 v186, v186
	v_exp_f32_e32 v187, v187
	s_nop 0
	v_pk_add_f32 v[184:185], v[184:185], v[242:243]
	v_pk_add_f32 v[186:187], v[186:187], v[242:243]
	v_rcp_f32_e32 v184, v184
	v_rcp_f32_e32 v185, v185
	v_rcp_f32_e32 v186, v186
	v_rcp_f32_e32 v187, v187
	s_nop 0
	v_pk_mul_f32 v[184:185], v[176:177], v[184:185]
	v_pk_mul_f32 v[186:187], v[178:179], v[186:187]
	v_pk_mul_f32 v[184:185], v[184:185], v[180:181]
; #define LAS __attribute__((address_space(3)))
; __device__ __forceinline__ unsigned cvt_pk_bf16(float lo, float hi) { const f32x2 v = {lo, hi}; return __builtin_bit_cast(unsigned, __builtin_convertvector(v, bf16x2_t)); }
;     __device__ __forceinline__ void operator()(Acc& acc, const Unit& u, int wr, int wc, int fr, int fq) const {
;     ...
; #pragma unroll
;         for (int n = 0; n < 2; ++n) {
;             const int col = u.pn * HALF + cl + 4 * n;
;             const f32x4 w0a = *(const f32x4*)(cw + col), w1a = *(const f32x4*)(cw + FF2 + col), w2a = *(const f32x4*)(cw + 2 * FF2 + col), bba = *(const f32x4*)(cb + col);
;             const f32x4 w0b = *(const f32x4*)(cw + FF + col), w1b = *(const f32x4*)(cw + FF2 + FF + col), w2b = *(const f32x4*)(cw + 2 * FF2 + FF + col), bbb = *(const f32x4*)(cb + FF + col);
; #pragma unroll
;             for (int ai = 0; ai < 2; ++ai) {
;                 const int s = ai * 2 + wr;
;                 f32x4 ha = (f32x4){0.f, 0.f, 0.f, 0.f}, hb = ha;
;                 if (s > 0 && fr >= 14) { ha = *(const LAS f32x4*)(halo + (((s - 1) * 2 + (fr - 14)) * 2 + 0) * HALF + cl + 4 * n);
;                                           hb = *(const LAS f32x4*)(halo + (((s - 1) * 2 + (fr - 14)) * 2 + 1) * HALF + cl + 4 * n); }
; #pragma unroll
;                 for (int m = 0; m < 4; ++m) {
;                     const f32x4 ca = acc[ai][0][m][n], cbv = acc[ai][1][m][n];
;                     const f32x4 pa = (m > 0) ? acc[ai][0][m > 0 ? m - 1 : 0][n] : ha, pb = (m > 0) ? acc[ai][1][m > 0 ? m - 1 : 0][n] : hb;
;                     float res[4];
; #pragma unroll
;                     for (int e = 0; e < 4; ++e) {
;                         const float a1 = dpp_prev1(ca[e], pa[e]), a2 = dpp_prev2(ca[e], pa[e]);
;                         const float b1 = dpp_prev1(cbv[e], pb[e]), b2 = dpp_prev2(cbv[e], pb[e]);
;                         const float ua = bba[e] + w0a[e] * a2 + w1a[e] * a1 + w2a[e] * ca[e];
;                         const float ub = bbb[e] + w0b[e] * b2 + w1b[e] * b1 + w2b[e] * cbv[e];
;                         res[e] = gelu_tanh(ua) * ub; }
;                     const int row = row0 + ai * HALF + m * 16;
;                     u32x2 w; w.x = cvt_pk_bf16(res[0], res[1]); w.y = cvt_pk_bf16(res[2], res[3]);
;                     *(u32x2*)(act + (size_t)row * FF + col) = w;
	v_pk_mul_f32 v[186:187], v[186:187], v[182:183]
	v_cvt_pk_bf16_f32 v213, v184, v185
	v_cvt_pk_bf16_f32 v215, v186, v187
	v_pk_fma_f32 v[176:177], v[112:113], v[152:153], v[156:157]
	v_pk_fma_f32 v[178:179], v[114:115], v[154:155], v[158:159]
	v_pk_fma_f32 v[180:181], v[120:121], v[136:137], v[140:141]
	v_pk_fma_f32 v[182:183], v[122:123], v[138:139], v[142:143]
	v_fmac_f32_dpp v176, v112, v148 row_shr:1 row_mask:0xf bank_mask:0xf bound_ctrl:1
	v_fmac_f32_dpp v177, v113, v149 row_shr:1 row_mask:0xf bank_mask:0xf bound_ctrl:1
	v_fmac_f32_dpp v178, v114, v150 row_shr:1 row_mask:0xf bank_mask:0xf bound_ctrl:1
	v_fmac_f32_dpp v179, v115, v151 row_shr:1 row_mask:0xf bank_mask:0xf bound_ctrl:1
	v_fmac_f32_dpp v176, v112, v144 row_shr:2 row_mask:0xf bank_mask:0xf bound_ctrl:1
	v_fmac_f32_dpp v177, v113, v145 row_shr:2 row_mask:0xf bank_mask:0xf bound_ctrl:1
	v_fmac_f32_dpp v178, v114, v146 row_shr:2 row_mask:0xf bank_mask:0xf bound_ctrl:1
	v_fmac_f32_dpp v179, v115, v147 row_shr:2 row_mask:0xf bank_mask:0xf bound_ctrl:1
	v_fmac_f32_dpp v176, v96, v148 row_shl:15 row_mask:0xf bank_mask:0xf bound_ctrl:1
	v_fmac_f32_dpp v177, v97, v149 row_shl:15 row_mask:0xf bank_mask:0xf bound_ctrl:1
	v_fmac_f32_dpp v178, v98, v150 row_shl:15 row_mask:0xf bank_mask:0xf bound_ctrl:1
	v_fmac_f32_dpp v179, v99, v151 row_shl:15 row_mask:0xf bank_mask:0xf bound_ctrl:1
	v_fmac_f32_dpp v176, v96, v144 row_shl:14 row_mask:0xf bank_mask:0xf bound_ctrl:1
	v_fmac_f32_dpp v177, v97, v145 row_shl:14 row_mask:0xf bank_mask:0xf bound_ctrl:1
	v_fmac_f32_dpp v178, v98, v146 row_shl:14 row_mask:0xf bank_mask:0xf bound_ctrl:1
	v_fmac_f32_dpp v179, v99, v147 row_shl:14 row_mask:0xf bank_mask:0xf bound_ctrl:1
	v_fmac_f32_dpp v180, v120, v132 row_shr:1 row_mask:0xf bank_mask:0xf bound_ctrl:1
	v_fmac_f32_dpp v181, v121, v133 row_shr:1 row_mask:0xf bank_mask:0xf bound_ctrl:1
	v_fmac_f32_dpp v182, v122, v134 row_shr:1 row_mask:0xf bank_mask:0xf bound_ctrl:1
	v_fmac_f32_dpp v183, v123, v135 row_shr:1 row_mask:0xf bank_mask:0xf bound_ctrl:1
	v_fmac_f32_dpp v180, v120, v128 row_shr:2 row_mask:0xf bank_mask:0xf bound_ctrl:1
	v_fmac_f32_dpp v181, v121, v129 row_shr:2 row_mask:0xf bank_mask:0xf bound_ctrl:1
	v_fmac_f32_dpp v182, v122, v130 row_shr:2 row_mask:0xf bank_mask:0xf bound_ctrl:1
	v_fmac_f32_dpp v183, v123, v131 row_shr:2 row_mask:0xf bank_mask:0xf bound_ctrl:1
	v_fmac_f32_dpp v180, v104, v132 row_shl:15 row_mask:0xf bank_mask:0xf bound_ctrl:1
	v_fmac_f32_dpp v181, v105, v133 row_shl:15 row_mask:0xf bank_mask:0xf bound_ctrl:1
	v_fmac_f32_dpp v182, v106, v134 row_shl:15 row_mask:0xf bank_mask:0xf bound_ctrl:1
	v_fmac_f32_dpp v183, v107, v135 row_shl:15 row_mask:0xf bank_mask:0xf bound_ctrl:1
	v_fmac_f32_dpp v180, v104, v128 row_shl:14 row_mask:0xf bank_mask:0xf bound_ctrl:1
	v_fmac_f32_dpp v181, v105, v129 row_shl:14 row_mask:0xf bank_mask:0xf bound_ctrl:1
	v_fmac_f32_dpp v182, v106, v130 row_shl:14 row_mask:0xf bank_mask:0xf bound_ctrl:1
	v_fmac_f32_dpp v183, v107, v131 row_shl:14 row_mask:0xf bank_mask:0xf bound_ctrl:1
	v_pk_mul_f32 v[184:185], v[176:177], v[176:177]
	v_pk_mul_f32 v[186:187], v[178:179], v[178:179]
	v_pk_fma_f32 v[184:185], v[184:185], v[238:239], v[240:241]
	v_pk_fma_f32 v[186:187], v[186:187], v[238:239], v[240:241]
	v_pk_mul_f32 v[184:185], v[176:177], v[184:185]
	v_pk_mul_f32 v[186:187], v[178:179], v[186:187]
	v_exp_f32_e32 v184, v184
	v_exp_f32_e32 v185, v185
	v_exp_f32_e32 v186, v186
	v_exp_f32_e32 v187, v187
	s_nop 0
	v_pk_add_f32 v[184:185], v[184:185], v[242:243]
	v_pk_add_f32 v[186:187], v[186:187], v[242:243]
	v_rcp_f32_e32 v184, v184
	v_rcp_f32_e32 v185, v185
	v_rcp_f32_e32 v186, v186
	v_rcp_f32_e32 v187, v187
	s_nop 0
	v_pk_mul_f32 v[184:185], v[176:177], v[184:185]
	v_pk_mul_f32 v[186:187], v[178:179], v[186:187]
	v_pk_mul_f32 v[184:185], v[184:185], v[180:181]
	v_pk_mul_f32 v[186:187], v[186:187], v[182:183]
	v_cvt_pk_bf16_f32 v217, v184, v185
	v_cvt_pk_bf16_f32 v219, v186, v187
	v_mov_b32_e32 v160, 0
	v_mov_b32_e32 v161, 0
	v_mov_b32_e32 v162, 0
	v_mov_b32_e32 v163, 0
	v_mov_b32_e32 v164, 0
	v_mov_b32_e32 v165, 0
	v_mov_b32_e32 v166, 0
	v_mov_b32_e32 v167, 0
	s_and_b64 s[42:43], s[26:27], s[6:7]
	s_and_saveexec_b64 s[56:57], s[42:43]
	s_cbranch_execz .Lcv_h10
	v_add_u32_e32 v168, 0xffffc010, v244
	v_add_u32_e32 v169, 0xffffc210, v244
	ds_read_b128 v[160:163], v168
	ds_read_b128 v[164:167], v169
; #define LAS __attribute__((address_space(3)))
; __device__ __forceinline__ unsigned cvt_pk_bf16(float lo, float hi) { const f32x2 v = {lo, hi}; return __builtin_bit_cast(unsigned, __builtin_convertvector(v, bf16x2_t)); }
;     __device__ __forceinline__ void operator()(Acc& acc, const Unit& u, int wr, int wc, int fr, int fq) const {
;     ...
;             const f32x4 w0a = *(const f32x4*)(cw + col), w1a = *(const f32x4*)(cw + FF2 + col), w2a = *(const f32x4*)(cw + 2 * FF2 + col), bba = *(const f32x4*)(cb + col);
;             const f32x4 w0b = *(const f32x4*)(cw + FF + col), w1b = *(const f32x4*)(cw + FF2 + FF + col), w2b = *(const f32x4*)(cw + 2 * FF2 + FF + col), bbb = *(const f32x4*)(cb + FF + col);
; #pragma unroll
;             for (int ai = 0; ai < 2; ++ai) {
;                 const int s = ai * 2 + wr;
;                 f32x4 ha = (f32x4){0.f, 0.f, 0.f, 0.f}, hb = ha;
;                 if (s > 0 && fr >= 14) { ha = *(const LAS f32x4*)(halo + (((s - 1) * 2 + (fr - 14)) * 2 + 0) * HALF + cl + 4 * n);
;                                           hb = *(const LAS f32x4*)(halo + (((s - 1) * 2 + (fr - 14)) * 2 + 1) * HALF + cl + 4 * n); }
; #pragma unroll
;                 for (int m = 0; m < 4; ++m) {
;                     const f32x4 ca = acc[ai][0][m][n], cbv = acc[ai][1][m][n];
;                     const f32x4 pa = (m > 0) ? acc[ai][0][m > 0 ? m - 1 : 0][n] : ha, pb = (m > 0) ? acc[ai][1][m > 0 ? m - 1 : 0][n] : hb;
;                     float res[4];
; #pragma unroll
;                     for (int e = 0; e < 4; ++e) {
;                         const float a1 = dpp_prev1(ca[e], pa[e]), a2 = dpp_prev2(ca[e], pa[e]);
;                         const float b1 = dpp_prev1(cbv[e], pb[e]), b2 = dpp_prev2(cbv[e], pb[e]);
;                         const float ua = bba[e] + w0a[e] * a2 + w1a[e] * a1 + w2a[e] * ca[e];
;                         const float ub = bbb[e] + w0b[e] * b2 + w1b[e] * b1 + w2b[e] * cbv[e];
;                         res[e] = gelu_tanh(ua) * ub; }
;                     const int row = row0 + ai * HALF + m * 16;
;                     u32x2 w; w.x = cvt_pk_bf16(res[0], res[1]); w.y = cvt_pk_bf16(res[2], res[3]);
;                     *(u32x2*)(act + (size_t)row * FF + col) = w;
.Lcv_h10:
	s_or_b64 exec, exec, s[56:57]
	s_waitcnt vmcnt(0) lgkmcnt(0)
	v_pk_fma_f32 v[176:177], v[12:13], v[40:41], v[56:57]
	v_pk_fma_f32 v[178:179], v[14:15], v[42:43], v[58:59]
	v_pk_fma_f32 v[180:181], v[4:5], v[32:33], v[48:49]
	v_pk_fma_f32 v[182:183], v[6:7], v[34:35], v[50:51]
	v_fmac_f32_dpp v176, v12, v24 row_shr:1 row_mask:0xf bank_mask:0xf bound_ctrl:1
	v_fmac_f32_dpp v177, v13, v25 row_shr:1 row_mask:0xf bank_mask:0xf bound_ctrl:1
	v_fmac_f32_dpp v178, v14, v26 row_shr:1 row_mask:0xf bank_mask:0xf bound_ctrl:1
	v_fmac_f32_dpp v179, v15, v27 row_shr:1 row_mask:0xf bank_mask:0xf bound_ctrl:1
	v_fmac_f32_dpp v176, v12, v8 row_shr:2 row_mask:0xf bank_mask:0xf bound_ctrl:1
	v_fmac_f32_dpp v177, v13, v9 row_shr:2 row_mask:0xf bank_mask:0xf bound_ctrl:1
	v_fmac_f32_dpp v178, v14, v10 row_shr:2 row_mask:0xf bank_mask:0xf bound_ctrl:1
	v_fmac_f32_dpp v179, v15, v11 row_shr:2 row_mask:0xf bank_mask:0xf bound_ctrl:1
	v_fmac_f32_dpp v176, v160, v24 row_shl:15 row_mask:0xf bank_mask:0xf bound_ctrl:1
	v_fmac_f32_dpp v177, v161, v25 row_shl:15 row_mask:0xf bank_mask:0xf bound_ctrl:1
	v_fmac_f32_dpp v178, v162, v26 row_shl:15 row_mask:0xf bank_mask:0xf bound_ctrl:1
	v_fmac_f32_dpp v179, v163, v27 row_shl:15 row_mask:0xf bank_mask:0xf bound_ctrl:1
	v_fmac_f32_dpp v176, v160, v8 row_shl:14 row_mask:0xf bank_mask:0xf bound_ctrl:1
	v_fmac_f32_dpp v177, v161, v9 row_shl:14 row_mask:0xf bank_mask:0xf bound_ctrl:1
	v_fmac_f32_dpp v178, v162, v10 row_shl:14 row_mask:0xf bank_mask:0xf bound_ctrl:1
	v_fmac_f32_dpp v179, v163, v11 row_shl:14 row_mask:0xf bank_mask:0xf bound_ctrl:1
	v_fmac_f32_dpp v180, v4, v16 row_shr:1 row_mask:0xf bank_mask:0xf bound_ctrl:1
	v_fmac_f32_dpp v181, v5, v17 row_shr:1 row_mask:0xf bank_mask:0xf bound_ctrl:1
	v_fmac_f32_dpp v182, v6, v18 row_shr:1 row_mask:0xf bank_mask:0xf bound_ctrl:1
	v_fmac_f32_dpp v183, v7, v19 row_shr:1 row_mask:0xf bank_mask:0xf bound_ctrl:1
	v_fmac_f32_dpp v180, v4, v0 row_shr:2 row_mask:0xf bank_mask:0xf bound_ctrl:1
	v_fmac_f32_dpp v181, v5, v1 row_shr:2 row_mask:0xf bank_mask:0xf bound_ctrl:1
	v_fmac_f32_dpp v182, v6, v2 row_shr:2 row_mask:0xf bank_mask:0xf bound_ctrl:1
	v_fmac_f32_dpp v183, v7, v3 row_shr:2 row_mask:0xf bank_mask:0xf bound_ctrl:1
	v_fmac_f32_dpp v180, v164, v16 row_shl:15 row_mask:0xf bank_mask:0xf bound_ctrl:1
	v_fmac_f32_dpp v181, v165, v17 row_shl:15 row_mask:0xf bank_mask:0xf bound_ctrl:1
	v_fmac_f32_dpp v182, v166, v18 row_shl:15 row_mask:0xf bank_mask:0xf bound_ctrl:1
	v_fmac_f32_dpp v183, v167, v19 row_shl:15 row_mask:0xf bank_mask:0xf bound_ctrl:1
	v_fmac_f32_dpp v180, v164, v0 row_shl:14 row_mask:0xf bank_mask:0xf bound_ctrl:1
	v_fmac_f32_dpp v181, v165, v1 row_shl:14 row_mask:0xf bank_mask:0xf bound_ctrl:1
	v_fmac_f32_dpp v182, v166, v2 row_shl:14 row_mask:0xf bank_mask:0xf bound_ctrl:1
	v_fmac_f32_dpp v183, v167, v3 row_shl:14 row_mask:0xf bank_mask:0xf bound_ctrl:1
	v_pk_mul_f32 v[184:185], v[176:177], v[176:177]
	v_pk_mul_f32 v[186:187], v[178:179], v[178:179]
	v_pk_fma_f32 v[184:185], v[184:185], v[238:239], v[240:241]
	v_pk_fma_f32 v[186:187], v[186:187], v[238:239], v[240:241]
	v_pk_mul_f32 v[184:185], v[176:177], v[184:185]
	v_pk_mul_f32 v[186:187], v[178:179], v[186:187]
	v_exp_f32_e32 v184, v184
	v_exp_f32_e32 v185, v185
	v_exp_f32_e32 v186, v186
	v_exp_f32_e32 v187, v187
	s_nop 0
	v_pk_add_f32 v[184:185], v[184:185], v[242:243]
	v_pk_add_f32 v[186:187], v[186:187], v[242:243]
	v_rcp_f32_e32 v184, v184
	v_rcp_f32_e32 v185, v185
	v_rcp_f32_e32 v186, v186
	v_rcp_f32_e32 v187, v187
	v_mad_i64_i32 v[168:169], s[0:1], v210, s88, v[246:247]
	v_pk_mul_f32 v[184:185], v[176:177], v[184:185]
	v_pk_mul_f32 v[186:187], v[178:179], v[186:187]
	v_pk_mul_f32 v[184:185], v[184:185], v[180:181]
	v_pk_mul_f32 v[186:187], v[186:187], v[182:183]
	v_mov_b32_e32 v188, v170
	v_mov_b32_e32 v189, v171
	v_cvt_pk_bf16_f32 v190, v184, v185
	v_cvt_pk_bf16_f32 v191, v186, v187
	global_store_dwordx4 v[168:169], v[188:191], off
	v_pk_fma_f32 v[176:177], v[28:29], v[40:41], v[56:57]
	v_pk_fma_f32 v[178:179], v[30:31], v[42:43], v[58:59]
	v_pk_fma_f32 v[180:181], v[20:21], v[32:33], v[48:49]
	v_pk_fma_f32 v[182:183], v[22:23], v[34:35], v[50:51]
	v_fmac_f32_dpp v176, v28, v24 row_shr:1 row_mask:0xf bank_mask:0xf bound_ctrl:1
	v_fmac_f32_dpp v177, v29, v25 row_shr:1 row_mask:0xf bank_mask:0xf bound_ctrl:1
	v_fmac_f32_dpp v178, v30, v26 row_shr:1 row_mask:0xf bank_mask:0xf bound_ctrl:1
	v_fmac_f32_dpp v179, v31, v27 row_shr:1 row_mask:0xf bank_mask:0xf bound_ctrl:1
	v_fmac_f32_dpp v176, v28, v8 row_shr:2 row_mask:0xf bank_mask:0xf bound_ctrl:1
	v_fmac_f32_dpp v177, v29, v9 row_shr:2 row_mask:0xf bank_mask:0xf bound_ctrl:1
	v_fmac_f32_dpp v178, v30, v10 row_shr:2 row_mask:0xf bank_mask:0xf bound_ctrl:1
	v_fmac_f32_dpp v179, v31, v11 row_shr:2 row_mask:0xf bank_mask:0xf bound_ctrl:1
	v_fmac_f32_dpp v176, v12, v24 row_shl:15 row_mask:0xf bank_mask:0xf bound_ctrl:1
	v_fmac_f32_dpp v177, v13, v25 row_shl:15 row_mask:0xf bank_mask:0xf bound_ctrl:1
	v_fmac_f32_dpp v178, v14, v26 row_shl:15 row_mask:0xf bank_mask:0xf bound_ctrl:1
	v_fmac_f32_dpp v179, v15, v27 row_shl:15 row_mask:0xf bank_mask:0xf bound_ctrl:1
	v_fmac_f32_dpp v176, v12, v8 row_shl:14 row_mask:0xf bank_mask:0xf bound_ctrl:1
	v_fmac_f32_dpp v177, v13, v9 row_shl:14 row_mask:0xf bank_mask:0xf bound_ctrl:1
	v_fmac_f32_dpp v178, v14, v10 row_shl:14 row_mask:0xf bank_mask:0xf bound_ctrl:1
	v_fmac_f32_dpp v179, v15, v11 row_shl:14 row_mask:0xf bank_mask:0xf bound_ctrl:1
	v_fmac_f32_dpp v180, v20, v16 row_shr:1 row_mask:0xf bank_mask:0xf bound_ctrl:1
	v_fmac_f32_dpp v181, v21, v17 row_shr:1 row_mask:0xf bank_mask:0xf bound_ctrl:1
; #define LAS __attribute__((address_space(3)))
; __device__ __forceinline__ unsigned cvt_pk_bf16(float lo, float hi) { const f32x2 v = {lo, hi}; return __builtin_bit_cast(unsigned, __builtin_convertvector(v, bf16x2_t)); }
;     __device__ __forceinline__ void operator()(Acc& acc, const Unit& u, int wr, int wc, int fr, int fq) const {
;     ...
;             for (int ai = 0; ai < 2; ++ai) {
;                 const int s = ai * 2 + wr;
;                 f32x4 ha = (f32x4){0.f, 0.f, 0.f, 0.f}, hb = ha;
;                 if (s > 0 && fr >= 14) { ha = *(const LAS f32x4*)(halo + (((s - 1) * 2 + (fr - 14)) * 2 + 0) * HALF + cl + 4 * n);
;                                           hb = *(const LAS f32x4*)(halo + (((s - 1) * 2 + (fr - 14)) * 2 + 1) * HALF + cl + 4 * n); }
; #pragma unroll
;                 for (int m = 0; m < 4; ++m) {
;                     const f32x4 ca = acc[ai][0][m][n], cbv = acc[ai][1][m][n];
;                     const f32x4 pa = (m > 0) ? acc[ai][0][m > 0 ? m - 1 : 0][n] : ha, pb = (m > 0) ? acc[ai][1][m > 0 ? m - 1 : 0][n] : hb;
;                     float res[4];
; #pragma unroll
;                     for (int e = 0; e < 4; ++e) {
;                         const float a1 = dpp_prev1(ca[e], pa[e]), a2 = dpp_prev2(ca[e], pa[e]);
;                         const float b1 = dpp_prev1(cbv[e], pb[e]), b2 = dpp_prev2(cbv[e], pb[e]);
;                         const float ua = bba[e] + w0a[e] * a2 + w1a[e] * a1 + w2a[e] * ca[e];
;                         const float ub = bbb[e] + w0b[e] * b2 + w1b[e] * b1 + w2b[e] * cbv[e];
;                         res[e] = gelu_tanh(ua) * ub; }
;                     const int row = row0 + ai * HALF + m * 16;
;                     u32x2 w; w.x = cvt_pk_bf16(res[0], res[1]); w.y = cvt_pk_bf16(res[2], res[3]);
;                     *(u32x2*)(act + (size_t)row * FF + col) = w;
	v_fmac_f32_dpp v182, v22, v18 row_shr:1 row_mask:0xf bank_mask:0xf bound_ctrl:1
	v_fmac_f32_dpp v183, v23, v19 row_shr:1 row_mask:0xf bank_mask:0xf bound_ctrl:1
	v_fmac_f32_dpp v180, v20, v0 row_shr:2 row_mask:0xf bank_mask:0xf bound_ctrl:1
	v_fmac_f32_dpp v181, v21, v1 row_shr:2 row_mask:0xf bank_mask:0xf bound_ctrl:1
	v_fmac_f32_dpp v182, v22, v2 row_shr:2 row_mask:0xf bank_mask:0xf bound_ctrl:1
	v_fmac_f32_dpp v183, v23, v3 row_shr:2 row_mask:0xf bank_mask:0xf bound_ctrl:1
	v_fmac_f32_dpp v180, v4, v16 row_shl:15 row_mask:0xf bank_mask:0xf bound_ctrl:1
	v_fmac_f32_dpp v181, v5, v17 row_shl:15 row_mask:0xf bank_mask:0xf bound_ctrl:1
	v_fmac_f32_dpp v182, v6, v18 row_shl:15 row_mask:0xf bank_mask:0xf bound_ctrl:1
	v_fmac_f32_dpp v183, v7, v19 row_shl:15 row_mask:0xf bank_mask:0xf bound_ctrl:1
	v_fmac_f32_dpp v180, v4, v0 row_shl:14 row_mask:0xf bank_mask:0xf bound_ctrl:1
	v_fmac_f32_dpp v181, v5, v1 row_shl:14 row_mask:0xf bank_mask:0xf bound_ctrl:1
	v_fmac_f32_dpp v182, v6, v2 row_shl:14 row_mask:0xf bank_mask:0xf bound_ctrl:1
	v_fmac_f32_dpp v183, v7, v3 row_shl:14 row_mask:0xf bank_mask:0xf bound_ctrl:1
	v_pk_mul_f32 v[184:185], v[176:177], v[176:177]
	v_pk_mul_f32 v[186:187], v[178:179], v[178:179]
	v_pk_fma_f32 v[184:185], v[184:185], v[238:239], v[240:241]
	v_pk_fma_f32 v[186:187], v[186:187], v[238:239], v[240:241]
	v_pk_mul_f32 v[184:185], v[176:177], v[184:185]
	v_pk_mul_f32 v[186:187], v[178:179], v[186:187]
	v_exp_f32_e32 v184, v184
	v_exp_f32_e32 v185, v185
	v_exp_f32_e32 v186, v186
	v_exp_f32_e32 v187, v187
	s_nop 0
	v_pk_add_f32 v[184:185], v[184:185], v[242:243]
	v_pk_add_f32 v[186:187], v[186:187], v[242:243]
	v_rcp_f32_e32 v184, v184
	v_rcp_f32_e32 v185, v185
	v_rcp_f32_e32 v186, v186
	v_rcp_f32_e32 v187, v187
	v_mad_i64_i32 v[168:169], s[0:1], v220, s88, v[246:247]
	v_pk_mul_f32 v[184:185], v[176:177], v[184:185]
	v_pk_mul_f32 v[186:187], v[178:179], v[186:187]
	v_pk_mul_f32 v[184:185], v[184:185], v[180:181]
	v_pk_mul_f32 v[186:187], v[186:187], v[182:183]
	v_mov_b32_e32 v188, v172
	v_mov_b32_e32 v189, v173
	v_cvt_pk_bf16_f32 v190, v184, v185
	v_cvt_pk_bf16_f32 v191, v186, v187
	global_store_dwordx4 v[168:169], v[188:191], off
	v_pk_fma_f32 v[176:177], v[44:45], v[40:41], v[56:57]
	v_pk_fma_f32 v[178:179], v[46:47], v[42:43], v[58:59]
	v_pk_fma_f32 v[180:181], v[36:37], v[32:33], v[48:49]
	v_pk_fma_f32 v[182:183], v[38:39], v[34:35], v[50:51]
	v_fmac_f32_dpp v176, v44, v24 row_shr:1 row_mask:0xf bank_mask:0xf bound_ctrl:1
	v_fmac_f32_dpp v177, v45, v25 row_shr:1 row_mask:0xf bank_mask:0xf bound_ctrl:1
	v_fmac_f32_dpp v178, v46, v26 row_shr:1 row_mask:0xf bank_mask:0xf bound_ctrl:1
	v_fmac_f32_dpp v179, v47, v27 row_shr:1 row_mask:0xf bank_mask:0xf bound_ctrl:1
	v_fmac_f32_dpp v176, v44, v8 row_shr:2 row_mask:0xf bank_mask:0xf bound_ctrl:1
	v_fmac_f32_dpp v177, v45, v9 row_shr:2 row_mask:0xf bank_mask:0xf bound_ctrl:1
	v_fmac_f32_dpp v178, v46, v10 row_shr:2 row_mask:0xf bank_mask:0xf bound_ctrl:1
	v_fmac_f32_dpp v179, v47, v11 row_shr:2 row_mask:0xf bank_mask:0xf bound_ctrl:1
	v_fmac_f32_dpp v176, v28, v24 row_shl:15 row_mask:0xf bank_mask:0xf bound_ctrl:1
	v_fmac_f32_dpp v177, v29, v25 row_shl:15 row_mask:0xf bank_mask:0xf bound_ctrl:1
	v_fmac_f32_dpp v178, v30, v26 row_shl:15 row_mask:0xf bank_mask:0xf bound_ctrl:1
	v_fmac_f32_dpp v179, v31, v27 row_shl:15 row_mask:0xf bank_mask:0xf bound_ctrl:1
	v_fmac_f32_dpp v176, v28, v8 row_shl:14 row_mask:0xf bank_mask:0xf bound_ctrl:1
	v_fmac_f32_dpp v177, v29, v9 row_shl:14 row_mask:0xf bank_mask:0xf bound_ctrl:1
	v_fmac_f32_dpp v178, v30, v10 row_shl:14 row_mask:0xf bank_mask:0xf bound_ctrl:1
	v_fmac_f32_dpp v179, v31, v11 row_shl:14 row_mask:0xf bank_mask:0xf bound_ctrl:1
	v_fmac_f32_dpp v180, v36, v16 row_shr:1 row_mask:0xf bank_mask:0xf bound_ctrl:1
	v_fmac_f32_dpp v181, v37, v17 row_shr:1 row_mask:0xf bank_mask:0xf bound_ctrl:1
	v_fmac_f32_dpp v182, v38, v18 row_shr:1 row_mask:0xf bank_mask:0xf bound_ctrl:1
	v_fmac_f32_dpp v183, v39, v19 row_shr:1 row_mask:0xf bank_mask:0xf bound_ctrl:1
	v_fmac_f32_dpp v180, v36, v0 row_shr:2 row_mask:0xf bank_mask:0xf bound_ctrl:1
	v_fmac_f32_dpp v181, v37, v1 row_shr:2 row_mask:0xf bank_mask:0xf bound_ctrl:1
	v_fmac_f32_dpp v182, v38, v2 row_shr:2 row_mask:0xf bank_mask:0xf bound_ctrl:1
	v_fmac_f32_dpp v183, v39, v3 row_shr:2 row_mask:0xf bank_mask:0xf bound_ctrl:1
	v_fmac_f32_dpp v180, v20, v16 row_shl:15 row_mask:0xf bank_mask:0xf bound_ctrl:1
	v_fmac_f32_dpp v181, v21, v17 row_shl:15 row_mask:0xf bank_mask:0xf bound_ctrl:1
	v_fmac_f32_dpp v182, v22, v18 row_shl:15 row_mask:0xf bank_mask:0xf bound_ctrl:1
	v_fmac_f32_dpp v183, v23, v19 row_shl:15 row_mask:0xf bank_mask:0xf bound_ctrl:1
	v_fmac_f32_dpp v180, v20, v0 row_shl:14 row_mask:0xf bank_mask:0xf bound_ctrl:1
	v_fmac_f32_dpp v181, v21, v1 row_shl:14 row_mask:0xf bank_mask:0xf bound_ctrl:1
	v_fmac_f32_dpp v182, v22, v2 row_shl:14 row_mask:0xf bank_mask:0xf bound_ctrl:1
	v_fmac_f32_dpp v183, v23, v3 row_shl:14 row_mask:0xf bank_mask:0xf bound_ctrl:1
	v_pk_mul_f32 v[184:185], v[176:177], v[176:177]
	v_pk_mul_f32 v[186:187], v[178:179], v[178:179]
	v_pk_fma_f32 v[184:185], v[184:185], v[238:239], v[240:241]
	v_pk_fma_f32 v[186:187], v[186:187], v[238:239], v[240:241]
	v_pk_mul_f32 v[184:185], v[176:177], v[184:185]
	v_pk_mul_f32 v[186:187], v[178:179], v[186:187]
	v_exp_f32_e32 v184, v184
	v_exp_f32_e32 v185, v185
	v_exp_f32_e32 v186, v186
	v_exp_f32_e32 v187, v187
	s_nop 0
	v_pk_add_f32 v[184:185], v[184:185], v[242:243]
	v_pk_add_f32 v[186:187], v[186:187], v[242:243]
	v_rcp_f32_e32 v184, v184
	v_rcp_f32_e32 v185, v185
	v_rcp_f32_e32 v186, v186
	v_rcp_f32_e32 v187, v187
; #define LAS __attribute__((address_space(3)))
; __device__ __forceinline__ unsigned cvt_pk_bf16(float lo, float hi) { const f32x2 v = {lo, hi}; return __builtin_bit_cast(unsigned, __builtin_convertvector(v, bf16x2_t)); }
;     __device__ __forceinline__ void operator()(Acc& acc, const Unit& u, int wr, int wc, int fr, int fq) const {
;     ...
;             for (int ai = 0; ai < 2; ++ai) {
;                 const int s = ai * 2 + wr;
;                 f32x4 ha = (f32x4){0.f, 0.f, 0.f, 0.f}, hb = ha;
;                 if (s > 0 && fr >= 14) { ha = *(const LAS f32x4*)(halo + (((s - 1) * 2 + (fr - 14)) * 2 + 0) * HALF + cl + 4 * n);
;                                           hb = *(const LAS f32x4*)(halo + (((s - 1) * 2 + (fr - 14)) * 2 + 1) * HALF + cl + 4 * n); }
; #pragma unroll
;                 for (int m = 0; m < 4; ++m) {
;                     const f32x4 ca = acc[ai][0][m][n], cbv = acc[ai][1][m][n];
;                     const f32x4 pa = (m > 0) ? acc[ai][0][m > 0 ? m - 1 : 0][n] : ha, pb = (m > 0) ? acc[ai][1][m > 0 ? m - 1 : 0][n] : hb;
;                     float res[4];
; #pragma unroll
;                     for (int e = 0; e < 4; ++e) {
;                         const float a1 = dpp_prev1(ca[e], pa[e]), a2 = dpp_prev2(ca[e], pa[e]);
;                         const float b1 = dpp_prev1(cbv[e], pb[e]), b2 = dpp_prev2(cbv[e], pb[e]);
;                         const float ua = bba[e] + w0a[e] * a2 + w1a[e] * a1 + w2a[e] * ca[e];
;                         const float ub = bbb[e] + w0b[e] * b2 + w1b[e] * b1 + w2b[e] * cbv[e];
;                         res[e] = gelu_tanh(ua) * ub; }
;                     const int row = row0 + ai * HALF + m * 16;
;                     u32x2 w; w.x = cvt_pk_bf16(res[0], res[1]); w.y = cvt_pk_bf16(res[2], res[3]);
;                     *(u32x2*)(act + (size_t)row * FF + col) = w;
	v_mad_i64_i32 v[168:169], s[0:1], v214, s88, v[246:247]
	v_pk_mul_f32 v[184:185], v[176:177], v[184:185]
	v_pk_mul_f32 v[186:187], v[178:179], v[186:187]
	v_pk_mul_f32 v[184:185], v[184:185], v[180:181]
	v_pk_mul_f32 v[186:187], v[186:187], v[182:183]
	v_mov_b32_e32 v188, v174
	v_mov_b32_e32 v189, v175
	v_cvt_pk_bf16_f32 v190, v184, v185
	v_cvt_pk_bf16_f32 v191, v186, v187
	global_store_dwordx4 v[168:169], v[188:191], off
	v_pk_fma_f32 v[176:177], v[60:61], v[40:41], v[56:57]
	v_pk_fma_f32 v[178:179], v[62:63], v[42:43], v[58:59]
	v_pk_fma_f32 v[180:181], v[52:53], v[32:33], v[48:49]
	v_pk_fma_f32 v[182:183], v[54:55], v[34:35], v[50:51]
	v_fmac_f32_dpp v176, v60, v24 row_shr:1 row_mask:0xf bank_mask:0xf bound_ctrl:1
	v_fmac_f32_dpp v177, v61, v25 row_shr:1 row_mask:0xf bank_mask:0xf bound_ctrl:1
	v_fmac_f32_dpp v178, v62, v26 row_shr:1 row_mask:0xf bank_mask:0xf bound_ctrl:1
	v_fmac_f32_dpp v179, v63, v27 row_shr:1 row_mask:0xf bank_mask:0xf bound_ctrl:1
	v_fmac_f32_dpp v176, v60, v8 row_shr:2 row_mask:0xf bank_mask:0xf bound_ctrl:1
	v_fmac_f32_dpp v177, v61, v9 row_shr:2 row_mask:0xf bank_mask:0xf bound_ctrl:1
	v_fmac_f32_dpp v178, v62, v10 row_shr:2 row_mask:0xf bank_mask:0xf bound_ctrl:1
	v_fmac_f32_dpp v179, v63, v11 row_shr:2 row_mask:0xf bank_mask:0xf bound_ctrl:1
	v_fmac_f32_dpp v176, v44, v24 row_shl:15 row_mask:0xf bank_mask:0xf bound_ctrl:1
	v_fmac_f32_dpp v177, v45, v25 row_shl:15 row_mask:0xf bank_mask:0xf bound_ctrl:1
	v_fmac_f32_dpp v178, v46, v26 row_shl:15 row_mask:0xf bank_mask:0xf bound_ctrl:1
	v_fmac_f32_dpp v179, v47, v27 row_shl:15 row_mask:0xf bank_mask:0xf bound_ctrl:1
	v_fmac_f32_dpp v176, v44, v8 row_shl:14 row_mask:0xf bank_mask:0xf bound_ctrl:1
	v_fmac_f32_dpp v177, v45, v9 row_shl:14 row_mask:0xf bank_mask:0xf bound_ctrl:1
	v_fmac_f32_dpp v178, v46, v10 row_shl:14 row_mask:0xf bank_mask:0xf bound_ctrl:1
	v_fmac_f32_dpp v179, v47, v11 row_shl:14 row_mask:0xf bank_mask:0xf bound_ctrl:1
	v_fmac_f32_dpp v180, v52, v16 row_shr:1 row_mask:0xf bank_mask:0xf bound_ctrl:1
	v_fmac_f32_dpp v181, v53, v17 row_shr:1 row_mask:0xf bank_mask:0xf bound_ctrl:1
	v_fmac_f32_dpp v182, v54, v18 row_shr:1 row_mask:0xf bank_mask:0xf bound_ctrl:1
	v_fmac_f32_dpp v183, v55, v19 row_shr:1 row_mask:0xf bank_mask:0xf bound_ctrl:1
	v_fmac_f32_dpp v180, v52, v0 row_shr:2 row_mask:0xf bank_mask:0xf bound_ctrl:1
	v_fmac_f32_dpp v181, v53, v1 row_shr:2 row_mask:0xf bank_mask:0xf bound_ctrl:1
	v_fmac_f32_dpp v182, v54, v2 row_shr:2 row_mask:0xf bank_mask:0xf bound_ctrl:1
	v_fmac_f32_dpp v183, v55, v3 row_shr:2 row_mask:0xf bank_mask:0xf bound_ctrl:1
	v_fmac_f32_dpp v180, v36, v16 row_shl:15 row_mask:0xf bank_mask:0xf bound_ctrl:1
	v_fmac_f32_dpp v181, v37, v17 row_shl:15 row_mask:0xf bank_mask:0xf bound_ctrl:1
	v_fmac_f32_dpp v182, v38, v18 row_shl:15 row_mask:0xf bank_mask:0xf bound_ctrl:1
	v_fmac_f32_dpp v183, v39, v19 row_shl:15 row_mask:0xf bank_mask:0xf bound_ctrl:1
	v_fmac_f32_dpp v180, v36, v0 row_shl:14 row_mask:0xf bank_mask:0xf bound_ctrl:1
	v_fmac_f32_dpp v181, v37, v1 row_shl:14 row_mask:0xf bank_mask:0xf bound_ctrl:1
	v_fmac_f32_dpp v182, v38, v2 row_shl:14 row_mask:0xf bank_mask:0xf bound_ctrl:1
	v_fmac_f32_dpp v183, v39, v3 row_shl:14 row_mask:0xf bank_mask:0xf bound_ctrl:1
	v_pk_mul_f32 v[184:185], v[176:177], v[176:177]
	v_pk_mul_f32 v[186:187], v[178:179], v[178:179]
	v_pk_fma_f32 v[184:185], v[184:185], v[238:239], v[240:241]
	v_pk_fma_f32 v[186:187], v[186:187], v[238:239], v[240:241]
	v_pk_mul_f32 v[184:185], v[176:177], v[184:185]
	v_pk_mul_f32 v[186:187], v[178:179], v[186:187]
	v_exp_f32_e32 v184, v184
	v_exp_f32_e32 v185, v185
	v_exp_f32_e32 v186, v186
	v_exp_f32_e32 v187, v187
	s_nop 0
	v_pk_add_f32 v[184:185], v[184:185], v[242:243]
	v_pk_add_f32 v[186:187], v[186:187], v[242:243]
	v_rcp_f32_e32 v184, v184
	v_rcp_f32_e32 v185, v185
	v_rcp_f32_e32 v186, v186
	v_rcp_f32_e32 v187, v187
	v_mad_i64_i32 v[168:169], s[0:1], v212, s88, v[246:247]
	v_pk_mul_f32 v[184:185], v[176:177], v[184:185]
	v_pk_mul_f32 v[186:187], v[178:179], v[186:187]
	v_pk_mul_f32 v[184:185], v[184:185], v[180:181]
	v_pk_mul_f32 v[186:187], v[186:187], v[182:183]
	v_mov_b32_e32 v188, v237
	v_mov_b32_e32 v189, v248
	v_cvt_pk_bf16_f32 v190, v184, v185
	v_cvt_pk_bf16_f32 v191, v186, v187
	global_store_dwordx4 v[168:169], v[188:191], off
	v_mov_b32_e32 v160, 0
	v_mov_b32_e32 v161, 0
	v_mov_b32_e32 v162, 0
	v_mov_b32_e32 v163, 0
	v_mov_b32_e32 v164, 0
	v_mov_b32_e32 v165, 0
	v_mov_b32_e32 v166, 0
	v_mov_b32_e32 v167, 0
	s_and_b64 s[42:43], s[28:29], s[6:7]
	s_and_saveexec_b64 s[56:57], s[42:43]
	s_cbranch_execz .Lcv_h11
	v_add_u32_e32 v168, 0xffffd010, v244
	v_add_u32_e32 v169, 0xffffd210, v244
	ds_read_b128 v[160:163], v168
	ds_read_b128 v[164:167], v169
; #define LAS __attribute__((address_space(3)))
; __device__ __forceinline__ unsigned cvt_pk_bf16(float lo, float hi) { const f32x2 v = {lo, hi}; return __builtin_bit_cast(unsigned, __builtin_convertvector(v, bf16x2_t)); }
;     __device__ __forceinline__ void operator()(Acc& acc, const Unit& u, int wr, int wc, int fr, int fq) const {
;     ...
;             for (int ai = 0; ai < 2; ++ai) {
;                 const int s = ai * 2 + wr;
;                 f32x4 ha = (f32x4){0.f, 0.f, 0.f, 0.f}, hb = ha;
;                 if (s > 0 && fr >= 14) { ha = *(const LAS f32x4*)(halo + (((s - 1) * 2 + (fr - 14)) * 2 + 0) * HALF + cl + 4 * n);
;                                           hb = *(const LAS f32x4*)(halo + (((s - 1) * 2 + (fr - 14)) * 2 + 1) * HALF + cl + 4 * n); }
; #pragma unroll
;                 for (int m = 0; m < 4; ++m) {
;                     const f32x4 ca = acc[ai][0][m][n], cbv = acc[ai][1][m][n];
;                     const f32x4 pa = (m > 0) ? acc[ai][0][m > 0 ? m - 1 : 0][n] : ha, pb = (m > 0) ? acc[ai][1][m > 0 ? m - 1 : 0][n] : hb;
;                     float res[4];
; #pragma unroll
;                     for (int e = 0; e < 4; ++e) {
;                         const float a1 = dpp_prev1(ca[e], pa[e]), a2 = dpp_prev2(ca[e], pa[e]);
;                         const float b1 = dpp_prev1(cbv[e], pb[e]), b2 = dpp_prev2(cbv[e], pb[e]);
;                         const float ua = bba[e] + w0a[e] * a2 + w1a[e] * a1 + w2a[e] * ca[e];
;                         const float ub = bbb[e] + w0b[e] * b2 + w1b[e] * b1 + w2b[e] * cbv[e];
;                         res[e] = gelu_tanh(ua) * ub; }
;                     const int row = row0 + ai * HALF + m * 16;
;                     u32x2 w; w.x = cvt_pk_bf16(res[0], res[1]); w.y = cvt_pk_bf16(res[2], res[3]);
;                     *(u32x2*)(act + (size_t)row * FF + col) = w;
.Lcv_h11:
	s_or_b64 exec, exec, s[56:57]
	s_waitcnt lgkmcnt(0)
	v_pk_fma_f32 v[176:177], v[68:69], v[40:41], v[56:57]
	v_pk_fma_f32 v[178:179], v[70:71], v[42:43], v[58:59]
	v_pk_fma_f32 v[180:181], v[76:77], v[32:33], v[48:49]
	v_pk_fma_f32 v[182:183], v[78:79], v[34:35], v[50:51]
	v_fmac_f32_dpp v176, v68, v24 row_shr:1 row_mask:0xf bank_mask:0xf bound_ctrl:1
	v_fmac_f32_dpp v177, v69, v25 row_shr:1 row_mask:0xf bank_mask:0xf bound_ctrl:1
	v_fmac_f32_dpp v178, v70, v26 row_shr:1 row_mask:0xf bank_mask:0xf bound_ctrl:1
	v_fmac_f32_dpp v179, v71, v27 row_shr:1 row_mask:0xf bank_mask:0xf bound_ctrl:1
	v_fmac_f32_dpp v176, v68, v8 row_shr:2 row_mask:0xf bank_mask:0xf bound_ctrl:1
	v_fmac_f32_dpp v177, v69, v9 row_shr:2 row_mask:0xf bank_mask:0xf bound_ctrl:1
	v_fmac_f32_dpp v178, v70, v10 row_shr:2 row_mask:0xf bank_mask:0xf bound_ctrl:1
	v_fmac_f32_dpp v179, v71, v11 row_shr:2 row_mask:0xf bank_mask:0xf bound_ctrl:1
	v_fmac_f32_dpp v176, v160, v24 row_shl:15 row_mask:0xf bank_mask:0xf bound_ctrl:1
	v_fmac_f32_dpp v177, v161, v25 row_shl:15 row_mask:0xf bank_mask:0xf bound_ctrl:1
	v_fmac_f32_dpp v178, v162, v26 row_shl:15 row_mask:0xf bank_mask:0xf bound_ctrl:1
	v_fmac_f32_dpp v179, v163, v27 row_shl:15 row_mask:0xf bank_mask:0xf bound_ctrl:1
	v_fmac_f32_dpp v176, v160, v8 row_shl:14 row_mask:0xf bank_mask:0xf bound_ctrl:1
	v_fmac_f32_dpp v177, v161, v9 row_shl:14 row_mask:0xf bank_mask:0xf bound_ctrl:1
	v_fmac_f32_dpp v178, v162, v10 row_shl:14 row_mask:0xf bank_mask:0xf bound_ctrl:1
	v_fmac_f32_dpp v179, v163, v11 row_shl:14 row_mask:0xf bank_mask:0xf bound_ctrl:1
	v_fmac_f32_dpp v180, v76, v16 row_shr:1 row_mask:0xf bank_mask:0xf bound_ctrl:1
	v_fmac_f32_dpp v181, v77, v17 row_shr:1 row_mask:0xf bank_mask:0xf bound_ctrl:1
	v_fmac_f32_dpp v182, v78, v18 row_shr:1 row_mask:0xf bank_mask:0xf bound_ctrl:1
	v_fmac_f32_dpp v183, v79, v19 row_shr:1 row_mask:0xf bank_mask:0xf bound_ctrl:1
	v_fmac_f32_dpp v180, v76, v0 row_shr:2 row_mask:0xf bank_mask:0xf bound_ctrl:1
	v_fmac_f32_dpp v181, v77, v1 row_shr:2 row_mask:0xf bank_mask:0xf bound_ctrl:1
	v_fmac_f32_dpp v182, v78, v2 row_shr:2 row_mask:0xf bank_mask:0xf bound_ctrl:1
	v_fmac_f32_dpp v183, v79, v3 row_shr:2 row_mask:0xf bank_mask:0xf bound_ctrl:1
	v_fmac_f32_dpp v180, v164, v16 row_shl:15 row_mask:0xf bank_mask:0xf bound_ctrl:1
	v_fmac_f32_dpp v181, v165, v17 row_shl:15 row_mask:0xf bank_mask:0xf bound_ctrl:1
	v_fmac_f32_dpp v182, v166, v18 row_shl:15 row_mask:0xf bank_mask:0xf bound_ctrl:1
	v_fmac_f32_dpp v183, v167, v19 row_shl:15 row_mask:0xf bank_mask:0xf bound_ctrl:1
	v_fmac_f32_dpp v180, v164, v0 row_shl:14 row_mask:0xf bank_mask:0xf bound_ctrl:1
	v_fmac_f32_dpp v181, v165, v1 row_shl:14 row_mask:0xf bank_mask:0xf bound_ctrl:1
	v_fmac_f32_dpp v182, v166, v2 row_shl:14 row_mask:0xf bank_mask:0xf bound_ctrl:1
	v_fmac_f32_dpp v183, v167, v3 row_shl:14 row_mask:0xf bank_mask:0xf bound_ctrl:1
	v_pk_mul_f32 v[184:185], v[176:177], v[176:177]
	v_pk_mul_f32 v[186:187], v[178:179], v[178:179]
	v_pk_fma_f32 v[184:185], v[184:185], v[238:239], v[240:241]
	v_pk_fma_f32 v[186:187], v[186:187], v[238:239], v[240:241]
	v_pk_mul_f32 v[184:185], v[176:177], v[184:185]
	v_pk_mul_f32 v[186:187], v[178:179], v[186:187]
	v_exp_f32_e32 v184, v184
	v_exp_f32_e32 v185, v185
	v_exp_f32_e32 v186, v186
	v_exp_f32_e32 v187, v187
	s_nop 0
	v_pk_add_f32 v[184:185], v[184:185], v[242:243]
	v_pk_add_f32 v[186:187], v[186:187], v[242:243]
	v_rcp_f32_e32 v184, v184
	v_rcp_f32_e32 v185, v185
	v_rcp_f32_e32 v186, v186
	v_rcp_f32_e32 v187, v187
	v_mad_i64_i32 v[168:169], s[0:1], v224, s88, v[246:247]
	v_pk_mul_f32 v[184:185], v[176:177], v[184:185]
	v_pk_mul_f32 v[186:187], v[178:179], v[186:187]
	v_pk_mul_f32 v[184:185], v[184:185], v[180:181]
	v_pk_mul_f32 v[186:187], v[186:187], v[182:183]
	v_mov_b32_e32 v188, v249
	v_mov_b32_e32 v189, v250
	v_cvt_pk_bf16_f32 v190, v184, v185
	v_cvt_pk_bf16_f32 v191, v186, v187
	global_store_dwordx4 v[168:169], v[188:191], off
	v_pk_fma_f32 v[176:177], v[84:85], v[40:41], v[56:57]
	v_pk_fma_f32 v[178:179], v[86:87], v[42:43], v[58:59]
	v_pk_fma_f32 v[180:181], v[92:93], v[32:33], v[48:49]
	v_pk_fma_f32 v[182:183], v[94:95], v[34:35], v[50:51]
	v_fmac_f32_dpp v176, v84, v24 row_shr:1 row_mask:0xf bank_mask:0xf bound_ctrl:1
	v_fmac_f32_dpp v177, v85, v25 row_shr:1 row_mask:0xf bank_mask:0xf bound_ctrl:1
	v_fmac_f32_dpp v178, v86, v26 row_shr:1 row_mask:0xf bank_mask:0xf bound_ctrl:1
	v_fmac_f32_dpp v179, v87, v27 row_shr:1 row_mask:0xf bank_mask:0xf bound_ctrl:1
	v_fmac_f32_dpp v176, v84, v8 row_shr:2 row_mask:0xf bank_mask:0xf bound_ctrl:1
	v_fmac_f32_dpp v177, v85, v9 row_shr:2 row_mask:0xf bank_mask:0xf bound_ctrl:1
	v_fmac_f32_dpp v178, v86, v10 row_shr:2 row_mask:0xf bank_mask:0xf bound_ctrl:1
	v_fmac_f32_dpp v179, v87, v11 row_shr:2 row_mask:0xf bank_mask:0xf bound_ctrl:1
	v_fmac_f32_dpp v176, v68, v24 row_shl:15 row_mask:0xf bank_mask:0xf bound_ctrl:1
	v_fmac_f32_dpp v177, v69, v25 row_shl:15 row_mask:0xf bank_mask:0xf bound_ctrl:1
	v_fmac_f32_dpp v178, v70, v26 row_shl:15 row_mask:0xf bank_mask:0xf bound_ctrl:1
	v_fmac_f32_dpp v179, v71, v27 row_shl:15 row_mask:0xf bank_mask:0xf bound_ctrl:1
	v_fmac_f32_dpp v176, v68, v8 row_shl:14 row_mask:0xf bank_mask:0xf bound_ctrl:1
	v_fmac_f32_dpp v177, v69, v9 row_shl:14 row_mask:0xf bank_mask:0xf bound_ctrl:1
	v_fmac_f32_dpp v178, v70, v10 row_shl:14 row_mask:0xf bank_mask:0xf bound_ctrl:1
	v_fmac_f32_dpp v179, v71, v11 row_shl:14 row_mask:0xf bank_mask:0xf bound_ctrl:1
	v_fmac_f32_dpp v180, v92, v16 row_shr:1 row_mask:0xf bank_mask:0xf bound_ctrl:1
	v_fmac_f32_dpp v181, v93, v17 row_shr:1 row_mask:0xf bank_mask:0xf bound_ctrl:1
; #define LAS __attribute__((address_space(3)))
; __device__ __forceinline__ unsigned cvt_pk_bf16(float lo, float hi) { const f32x2 v = {lo, hi}; return __builtin_bit_cast(unsigned, __builtin_convertvector(v, bf16x2_t)); }
;     __device__ __forceinline__ void operator()(Acc& acc, const Unit& u, int wr, int wc, int fr, int fq) const {
;     ...
;             for (int ai = 0; ai < 2; ++ai) {
;                 const int s = ai * 2 + wr;
;                 f32x4 ha = (f32x4){0.f, 0.f, 0.f, 0.f}, hb = ha;
;                 if (s > 0 && fr >= 14) { ha = *(const LAS f32x4*)(halo + (((s - 1) * 2 + (fr - 14)) * 2 + 0) * HALF + cl + 4 * n);
;                                           hb = *(const LAS f32x4*)(halo + (((s - 1) * 2 + (fr - 14)) * 2 + 1) * HALF + cl + 4 * n); }
; #pragma unroll
;                 for (int m = 0; m < 4; ++m) {
;                     const f32x4 ca = acc[ai][0][m][n], cbv = acc[ai][1][m][n];
;                     const f32x4 pa = (m > 0) ? acc[ai][0][m > 0 ? m - 1 : 0][n] : ha, pb = (m > 0) ? acc[ai][1][m > 0 ? m - 1 : 0][n] : hb;
;                     float res[4];
; #pragma unroll
;                     for (int e = 0; e < 4; ++e) {
;                         const float a1 = dpp_prev1(ca[e], pa[e]), a2 = dpp_prev2(ca[e], pa[e]);
;                         const float b1 = dpp_prev1(cbv[e], pb[e]), b2 = dpp_prev2(cbv[e], pb[e]);
;                         const float ua = bba[e] + w0a[e] * a2 + w1a[e] * a1 + w2a[e] * ca[e];
;                         const float ub = bbb[e] + w0b[e] * b2 + w1b[e] * b1 + w2b[e] * cbv[e];
;                         res[e] = gelu_tanh(ua) * ub; }
;                     const int row = row0 + ai * HALF + m * 16;
;                     u32x2 w; w.x = cvt_pk_bf16(res[0], res[1]); w.y = cvt_pk_bf16(res[2], res[3]);
;                     *(u32x2*)(act + (size_t)row * FF + col) = w;
	v_fmac_f32_dpp v182, v94, v18 row_shr:1 row_mask:0xf bank_mask:0xf bound_ctrl:1
	v_fmac_f32_dpp v183, v95, v19 row_shr:1 row_mask:0xf bank_mask:0xf bound_ctrl:1
	v_fmac_f32_dpp v180, v92, v0 row_shr:2 row_mask:0xf bank_mask:0xf bound_ctrl:1
	v_fmac_f32_dpp v181, v93, v1 row_shr:2 row_mask:0xf bank_mask:0xf bound_ctrl:1
	v_fmac_f32_dpp v182, v94, v2 row_shr:2 row_mask:0xf bank_mask:0xf bound_ctrl:1
	v_fmac_f32_dpp v183, v95, v3 row_shr:2 row_mask:0xf bank_mask:0xf bound_ctrl:1
	v_fmac_f32_dpp v180, v76, v16 row_shl:15 row_mask:0xf bank_mask:0xf bound_ctrl:1
	v_fmac_f32_dpp v181, v77, v17 row_shl:15 row_mask:0xf bank_mask:0xf bound_ctrl:1
	v_fmac_f32_dpp v182, v78, v18 row_shl:15 row_mask:0xf bank_mask:0xf bound_ctrl:1
	v_fmac_f32_dpp v183, v79, v19 row_shl:15 row_mask:0xf bank_mask:0xf bound_ctrl:1
	v_fmac_f32_dpp v180, v76, v0 row_shl:14 row_mask:0xf bank_mask:0xf bound_ctrl:1
	v_fmac_f32_dpp v181, v77, v1 row_shl:14 row_mask:0xf bank_mask:0xf bound_ctrl:1
	v_fmac_f32_dpp v182, v78, v2 row_shl:14 row_mask:0xf bank_mask:0xf bound_ctrl:1
	v_fmac_f32_dpp v183, v79, v3 row_shl:14 row_mask:0xf bank_mask:0xf bound_ctrl:1
	v_pk_mul_f32 v[184:185], v[176:177], v[176:177]
	v_pk_mul_f32 v[186:187], v[178:179], v[178:179]
	v_pk_fma_f32 v[184:185], v[184:185], v[238:239], v[240:241]
	v_pk_fma_f32 v[186:187], v[186:187], v[238:239], v[240:241]
	v_pk_mul_f32 v[184:185], v[176:177], v[184:185]
	v_pk_mul_f32 v[186:187], v[178:179], v[186:187]
	v_exp_f32_e32 v184, v184
	v_exp_f32_e32 v185, v185
	v_exp_f32_e32 v186, v186
	v_exp_f32_e32 v187, v187
	s_nop 0
	v_pk_add_f32 v[184:185], v[184:185], v[242:243]
	v_pk_add_f32 v[186:187], v[186:187], v[242:243]
	v_rcp_f32_e32 v184, v184
	v_rcp_f32_e32 v185, v185
	v_rcp_f32_e32 v186, v186
	v_rcp_f32_e32 v187, v187
	v_mad_i64_i32 v[168:169], s[0:1], v218, s88, v[246:247]
	v_pk_mul_f32 v[184:185], v[176:177], v[184:185]
	v_pk_mul_f32 v[186:187], v[178:179], v[186:187]
	v_pk_mul_f32 v[184:185], v[184:185], v[180:181]
	v_pk_mul_f32 v[186:187], v[186:187], v[182:183]
	v_mov_b32_e32 v188, v251
	v_mov_b32_e32 v189, v211
	v_cvt_pk_bf16_f32 v190, v184, v185
	v_cvt_pk_bf16_f32 v191, v186, v187
	global_store_dwordx4 v[168:169], v[188:191], off
	v_pk_fma_f32 v[176:177], v[100:101], v[40:41], v[56:57]
	v_pk_fma_f32 v[178:179], v[102:103], v[42:43], v[58:59]
	v_pk_fma_f32 v[180:181], v[108:109], v[32:33], v[48:49]
	v_pk_fma_f32 v[182:183], v[110:111], v[34:35], v[50:51]
	v_fmac_f32_dpp v176, v100, v24 row_shr:1 row_mask:0xf bank_mask:0xf bound_ctrl:1
	v_fmac_f32_dpp v177, v101, v25 row_shr:1 row_mask:0xf bank_mask:0xf bound_ctrl:1
	v_fmac_f32_dpp v178, v102, v26 row_shr:1 row_mask:0xf bank_mask:0xf bound_ctrl:1
	v_fmac_f32_dpp v179, v103, v27 row_shr:1 row_mask:0xf bank_mask:0xf bound_ctrl:1
	v_fmac_f32_dpp v176, v100, v8 row_shr:2 row_mask:0xf bank_mask:0xf bound_ctrl:1
	v_fmac_f32_dpp v177, v101, v9 row_shr:2 row_mask:0xf bank_mask:0xf bound_ctrl:1
	v_fmac_f32_dpp v178, v102, v10 row_shr:2 row_mask:0xf bank_mask:0xf bound_ctrl:1
	v_fmac_f32_dpp v179, v103, v11 row_shr:2 row_mask:0xf bank_mask:0xf bound_ctrl:1
	v_fmac_f32_dpp v176, v84, v24 row_shl:15 row_mask:0xf bank_mask:0xf bound_ctrl:1
	v_fmac_f32_dpp v177, v85, v25 row_shl:15 row_mask:0xf bank_mask:0xf bound_ctrl:1
	v_fmac_f32_dpp v178, v86, v26 row_shl:15 row_mask:0xf bank_mask:0xf bound_ctrl:1
	v_fmac_f32_dpp v179, v87, v27 row_shl:15 row_mask:0xf bank_mask:0xf bound_ctrl:1
	v_fmac_f32_dpp v176, v84, v8 row_shl:14 row_mask:0xf bank_mask:0xf bound_ctrl:1
	v_fmac_f32_dpp v177, v85, v9 row_shl:14 row_mask:0xf bank_mask:0xf bound_ctrl:1
	v_fmac_f32_dpp v178, v86, v10 row_shl:14 row_mask:0xf bank_mask:0xf bound_ctrl:1
	v_fmac_f32_dpp v179, v87, v11 row_shl:14 row_mask:0xf bank_mask:0xf bound_ctrl:1
	v_fmac_f32_dpp v180, v108, v16 row_shr:1 row_mask:0xf bank_mask:0xf bound_ctrl:1
	v_fmac_f32_dpp v181, v109, v17 row_shr:1 row_mask:0xf bank_mask:0xf bound_ctrl:1
	v_fmac_f32_dpp v182, v110, v18 row_shr:1 row_mask:0xf bank_mask:0xf bound_ctrl:1
	v_fmac_f32_dpp v183, v111, v19 row_shr:1 row_mask:0xf bank_mask:0xf bound_ctrl:1
	v_fmac_f32_dpp v180, v108, v0 row_shr:2 row_mask:0xf bank_mask:0xf bound_ctrl:1
	v_fmac_f32_dpp v181, v109, v1 row_shr:2 row_mask:0xf bank_mask:0xf bound_ctrl:1
	v_fmac_f32_dpp v182, v110, v2 row_shr:2 row_mask:0xf bank_mask:0xf bound_ctrl:1
	v_fmac_f32_dpp v183, v111, v3 row_shr:2 row_mask:0xf bank_mask:0xf bound_ctrl:1
	v_fmac_f32_dpp v180, v92, v16 row_shl:15 row_mask:0xf bank_mask:0xf bound_ctrl:1
	v_fmac_f32_dpp v181, v93, v17 row_shl:15 row_mask:0xf bank_mask:0xf bound_ctrl:1
	v_fmac_f32_dpp v182, v94, v18 row_shl:15 row_mask:0xf bank_mask:0xf bound_ctrl:1
	v_fmac_f32_dpp v183, v95, v19 row_shl:15 row_mask:0xf bank_mask:0xf bound_ctrl:1
	v_fmac_f32_dpp v180, v92, v0 row_shl:14 row_mask:0xf bank_mask:0xf bound_ctrl:1
	v_fmac_f32_dpp v181, v93, v1 row_shl:14 row_mask:0xf bank_mask:0xf bound_ctrl:1
	v_fmac_f32_dpp v182, v94, v2 row_shl:14 row_mask:0xf bank_mask:0xf bound_ctrl:1
	v_fmac_f32_dpp v183, v95, v3 row_shl:14 row_mask:0xf bank_mask:0xf bound_ctrl:1
; #define LAS __attribute__((address_space(3)))
; __device__ __forceinline__ unsigned cvt_pk_bf16(float lo, float hi) { const f32x2 v = {lo, hi}; return __builtin_bit_cast(unsigned, __builtin_convertvector(v, bf16x2_t)); }
;     __device__ __forceinline__ void operator()(Acc& acc, const Unit& u, int wr, int wc, int fr, int fq) const {
;     ...
;             for (int ai = 0; ai < 2; ++ai) {
;                 const int s = ai * 2 + wr;
;                 f32x4 ha = (f32x4){0.f, 0.f, 0.f, 0.f}, hb = ha;
;                 if (s > 0 && fr >= 14) { ha = *(const LAS f32x4*)(halo + (((s - 1) * 2 + (fr - 14)) * 2 + 0) * HALF + cl + 4 * n);
;                                           hb = *(const LAS f32x4*)(halo + (((s - 1) * 2 + (fr - 14)) * 2 + 1) * HALF + cl + 4 * n); }
; #pragma unroll
;                 for (int m = 0; m < 4; ++m) {
;                     const f32x4 ca = acc[ai][0][m][n], cbv = acc[ai][1][m][n];
;                     const f32x4 pa = (m > 0) ? acc[ai][0][m > 0 ? m - 1 : 0][n] : ha, pb = (m > 0) ? acc[ai][1][m > 0 ? m - 1 : 0][n] : hb;
;                     float res[4];
; #pragma unroll
;                     for (int e = 0; e < 4; ++e) {
;                         const float a1 = dpp_prev1(ca[e], pa[e]), a2 = dpp_prev2(ca[e], pa[e]);
;                         const float b1 = dpp_prev1(cbv[e], pb[e]), b2 = dpp_prev2(cbv[e], pb[e]);
;                         const float ua = bba[e] + w0a[e] * a2 + w1a[e] * a1 + w2a[e] * ca[e];
;                         const float ub = bbb[e] + w0b[e] * b2 + w1b[e] * b1 + w2b[e] * cbv[e];
;                         res[e] = gelu_tanh(ua) * ub; }
;                     const int row = row0 + ai * HALF + m * 16;
;                     u32x2 w; w.x = cvt_pk_bf16(res[0], res[1]); w.y = cvt_pk_bf16(res[2], res[3]);
;                     *(u32x2*)(act + (size_t)row * FF + col) = w;
	v_pk_mul_f32 v[184:185], v[176:177], v[176:177]
	v_pk_mul_f32 v[186:187], v[178:179], v[178:179]
	v_pk_fma_f32 v[184:185], v[184:185], v[238:239], v[240:241]
	v_pk_fma_f32 v[186:187], v[186:187], v[238:239], v[240:241]
	v_pk_mul_f32 v[184:185], v[176:177], v[184:185]
	v_pk_mul_f32 v[186:187], v[178:179], v[186:187]
	v_exp_f32_e32 v184, v184
	v_exp_f32_e32 v185, v185
	v_exp_f32_e32 v186, v186
	v_exp_f32_e32 v187, v187
	s_nop 0
	v_pk_add_f32 v[184:185], v[184:185], v[242:243]
	v_pk_add_f32 v[186:187], v[186:187], v[242:243]
	v_rcp_f32_e32 v184, v184
	v_rcp_f32_e32 v185, v185
	v_rcp_f32_e32 v186, v186
	v_rcp_f32_e32 v187, v187
	v_mad_i64_i32 v[168:169], s[0:1], v222, s88, v[246:247]
	v_pk_mul_f32 v[184:185], v[176:177], v[184:185]
	v_pk_mul_f32 v[186:187], v[178:179], v[186:187]
	v_pk_mul_f32 v[184:185], v[184:185], v[180:181]
	v_pk_mul_f32 v[186:187], v[186:187], v[182:183]
	v_mov_b32_e32 v188, v213
	v_mov_b32_e32 v189, v215
	v_cvt_pk_bf16_f32 v190, v184, v185
	v_cvt_pk_bf16_f32 v191, v186, v187
	global_store_dwordx4 v[168:169], v[188:191], off
	v_pk_fma_f32 v[176:177], v[116:117], v[40:41], v[56:57]
	v_pk_fma_f32 v[178:179], v[118:119], v[42:43], v[58:59]
	v_pk_fma_f32 v[180:181], v[124:125], v[32:33], v[48:49]
	v_pk_fma_f32 v[182:183], v[126:127], v[34:35], v[50:51]
	v_fmac_f32_dpp v176, v116, v24 row_shr:1 row_mask:0xf bank_mask:0xf bound_ctrl:1
	v_fmac_f32_dpp v177, v117, v25 row_shr:1 row_mask:0xf bank_mask:0xf bound_ctrl:1
	v_fmac_f32_dpp v178, v118, v26 row_shr:1 row_mask:0xf bank_mask:0xf bound_ctrl:1
	v_fmac_f32_dpp v179, v119, v27 row_shr:1 row_mask:0xf bank_mask:0xf bound_ctrl:1
	v_fmac_f32_dpp v176, v116, v8 row_shr:2 row_mask:0xf bank_mask:0xf bound_ctrl:1
	v_fmac_f32_dpp v177, v117, v9 row_shr:2 row_mask:0xf bank_mask:0xf bound_ctrl:1
	v_fmac_f32_dpp v178, v118, v10 row_shr:2 row_mask:0xf bank_mask:0xf bound_ctrl:1
	v_fmac_f32_dpp v179, v119, v11 row_shr:2 row_mask:0xf bank_mask:0xf bound_ctrl:1
	v_fmac_f32_dpp v176, v100, v24 row_shl:15 row_mask:0xf bank_mask:0xf bound_ctrl:1
	v_fmac_f32_dpp v177, v101, v25 row_shl:15 row_mask:0xf bank_mask:0xf bound_ctrl:1
	v_fmac_f32_dpp v178, v102, v26 row_shl:15 row_mask:0xf bank_mask:0xf bound_ctrl:1
	v_fmac_f32_dpp v179, v103, v27 row_shl:15 row_mask:0xf bank_mask:0xf bound_ctrl:1
	v_fmac_f32_dpp v176, v100, v8 row_shl:14 row_mask:0xf bank_mask:0xf bound_ctrl:1
	v_fmac_f32_dpp v177, v101, v9 row_shl:14 row_mask:0xf bank_mask:0xf bound_ctrl:1
	v_fmac_f32_dpp v178, v102, v10 row_shl:14 row_mask:0xf bank_mask:0xf bound_ctrl:1
	v_fmac_f32_dpp v179, v103, v11 row_shl:14 row_mask:0xf bank_mask:0xf bound_ctrl:1
	v_fmac_f32_dpp v180, v124, v16 row_shr:1 row_mask:0xf bank_mask:0xf bound_ctrl:1
	v_fmac_f32_dpp v181, v125, v17 row_shr:1 row_mask:0xf bank_mask:0xf bound_ctrl:1
	v_fmac_f32_dpp v182, v126, v18 row_shr:1 row_mask:0xf bank_mask:0xf bound_ctrl:1
	v_fmac_f32_dpp v183, v127, v19 row_shr:1 row_mask:0xf bank_mask:0xf bound_ctrl:1
	v_fmac_f32_dpp v180, v124, v0 row_shr:2 row_mask:0xf bank_mask:0xf bound_ctrl:1
	v_fmac_f32_dpp v181, v125, v1 row_shr:2 row_mask:0xf bank_mask:0xf bound_ctrl:1
	v_fmac_f32_dpp v182, v126, v2 row_shr:2 row_mask:0xf bank_mask:0xf bound_ctrl:1
	v_fmac_f32_dpp v183, v127, v3 row_shr:2 row_mask:0xf bank_mask:0xf bound_ctrl:1
	v_fmac_f32_dpp v180, v108, v16 row_shl:15 row_mask:0xf bank_mask:0xf bound_ctrl:1
	v_fmac_f32_dpp v181, v109, v17 row_shl:15 row_mask:0xf bank_mask:0xf bound_ctrl:1
	v_fmac_f32_dpp v182, v110, v18 row_shl:15 row_mask:0xf bank_mask:0xf bound_ctrl:1
	v_fmac_f32_dpp v183, v111, v19 row_shl:15 row_mask:0xf bank_mask:0xf bound_ctrl:1
	v_fmac_f32_dpp v180, v108, v0 row_shl:14 row_mask:0xf bank_mask:0xf bound_ctrl:1
	v_fmac_f32_dpp v181, v109, v1 row_shl:14 row_mask:0xf bank_mask:0xf bound_ctrl:1
	v_fmac_f32_dpp v182, v110, v2 row_shl:14 row_mask:0xf bank_mask:0xf bound_ctrl:1
	v_fmac_f32_dpp v183, v111, v3 row_shl:14 row_mask:0xf bank_mask:0xf bound_ctrl:1
	v_pk_mul_f32 v[184:185], v[176:177], v[176:177]
	v_pk_mul_f32 v[186:187], v[178:179], v[178:179]
	v_pk_fma_f32 v[184:185], v[184:185], v[238:239], v[240:241]
	v_pk_fma_f32 v[186:187], v[186:187], v[238:239], v[240:241]
	v_pk_mul_f32 v[184:185], v[176:177], v[184:185]
	v_pk_mul_f32 v[186:187], v[178:179], v[186:187]
	v_exp_f32_e32 v184, v184
	v_exp_f32_e32 v185, v185
	v_exp_f32_e32 v186, v186
	v_exp_f32_e32 v187, v187
	s_nop 0
	v_pk_add_f32 v[184:185], v[184:185], v[242:243]
	v_pk_add_f32 v[186:187], v[186:187], v[242:243]
	v_rcp_f32_e32 v184, v184
	v_rcp_f32_e32 v185, v185
	v_rcp_f32_e32 v186, v186
	v_rcp_f32_e32 v187, v187
	v_mad_i64_i32 v[168:169], s[0:1], v216, s88, v[246:247]
	v_pk_mul_f32 v[184:185], v[176:177], v[184:185]
	v_pk_mul_f32 v[186:187], v[178:179], v[186:187]
	v_pk_mul_f32 v[184:185], v[184:185], v[180:181]
	v_pk_mul_f32 v[186:187], v[186:187], v[182:183]
	v_mov_b32_e32 v188, v217
	v_mov_b32_e32 v189, v219
	v_cvt_pk_bf16_f32 v190, v184, v185
	v_cvt_pk_bf16_f32 v191, v186, v187
	global_store_dwordx4 v[168:169], v[188:191], off
